# P3 as 256 balanced 160-row units; its helper weight conversions relocated into idle tails of P2/P7/P9
# baseline (speedup 1.0000x reference)
.LBB0_181:
	v_add_u32_e32 v18, s1, v16
	v_add_u32_e32 v20, 2, v18
	v_add_u32_e32 v22, 4, v18
	v_add_u32_e32 v24, 6, v18
	v_ashrrev_i32_e32 v19, 31, v18
	v_add_u32_e32 v26, 8, v18
	v_add_u32_e32 v28, 10, v18
	v_add_u32_e32 v30, 12, v18
	v_add_u32_e32 v32, 14, v18
	v_ashrrev_i32_e32 v21, 31, v20
	v_ashrrev_i32_e32 v23, 31, v22
	v_ashrrev_i32_e32 v25, 31, v24
	v_lshlrev_b64 v[18:19], 12, v[18:19]
	v_ashrrev_i32_e32 v27, 31, v26
	v_ashrrev_i32_e32 v29, 31, v28
	v_ashrrev_i32_e32 v31, 31, v30
	v_ashrrev_i32_e32 v33, 31, v32
	v_lshlrev_b64 v[20:21], 12, v[20:21]
	v_lshlrev_b64 v[22:23], 12, v[22:23]
	v_lshlrev_b64 v[24:25], 12, v[24:25]
	v_lshl_add_u64 v[18:19], v[6:7], 0, v[18:19]
	v_lshlrev_b64 v[26:27], 12, v[26:27]
	v_lshlrev_b64 v[28:29], 12, v[28:29]
	v_lshlrev_b64 v[30:31], 12, v[30:31]
	v_lshlrev_b64 v[32:33], 12, v[32:33]
	v_lshl_add_u64 v[20:21], v[6:7], 0, v[20:21]
	v_lshl_add_u64 v[22:23], v[6:7], 0, v[22:23]
	v_lshl_add_u64 v[24:25], v[6:7], 0, v[24:25]
	v_lshl_add_u64 v[26:27], v[6:7], 0, v[26:27]
	v_lshl_add_u64 v[28:29], v[6:7], 0, v[28:29]
	v_lshl_add_u64 v[30:31], v[6:7], 0, v[30:31]
	v_lshl_add_u64 v[32:33], v[6:7], 0, v[32:33]
	global_load_dword v100, v[18:19], off nt
	s_nop 0
	global_load_dword v101, v[20:21], off nt
	s_nop 0
	global_load_dword v102, v[22:23], off nt
	global_load_dword v103, v[24:25], off nt
	s_nop 0
	global_load_dword v104, v[26:27], off nt
	global_load_dword v105, v[28:29], off nt
	global_load_dword v106, v[30:31], off nt
	global_load_dword v107, v[32:33], off nt
	s_add_i32 s1, s1, 16
	v_add_u32_e32 v18, s1, v16
	v_add_u32_e32 v20, 2, v18
	v_add_u32_e32 v22, 4, v18
	v_add_u32_e32 v24, 6, v18
	v_ashrrev_i32_e32 v19, 31, v18
	v_add_u32_e32 v26, 8, v18
	v_add_u32_e32 v28, 10, v18
	v_add_u32_e32 v30, 12, v18
	v_add_u32_e32 v32, 14, v18
	v_ashrrev_i32_e32 v21, 31, v20
	v_ashrrev_i32_e32 v23, 31, v22
	v_ashrrev_i32_e32 v25, 31, v24
	v_lshlrev_b64 v[18:19], 12, v[18:19]
	v_ashrrev_i32_e32 v27, 31, v26
	v_ashrrev_i32_e32 v29, 31, v28
	v_ashrrev_i32_e32 v31, 31, v30
	v_ashrrev_i32_e32 v33, 31, v32
	v_lshlrev_b64 v[20:21], 12, v[20:21]
	v_lshlrev_b64 v[22:23], 12, v[22:23]
	v_lshlrev_b64 v[24:25], 12, v[24:25]
	v_lshl_add_u64 v[18:19], v[6:7], 0, v[18:19]
	v_lshlrev_b64 v[26:27], 12, v[26:27]
	v_lshlrev_b64 v[28:29], 12, v[28:29]
	v_lshlrev_b64 v[30:31], 12, v[30:31]
	v_lshlrev_b64 v[32:33], 12, v[32:33]
	v_lshl_add_u64 v[20:21], v[6:7], 0, v[20:21]
	v_lshl_add_u64 v[22:23], v[6:7], 0, v[22:23]
	v_lshl_add_u64 v[24:25], v[6:7], 0, v[24:25]
	v_lshl_add_u64 v[26:27], v[6:7], 0, v[26:27]
	v_lshl_add_u64 v[28:29], v[6:7], 0, v[28:29]
	v_lshl_add_u64 v[30:31], v[6:7], 0, v[30:31]
	v_lshl_add_u64 v[32:33], v[6:7], 0, v[32:33]
	global_load_dword v108, v[18:19], off nt
	s_nop 0
	global_load_dword v109, v[20:21], off nt
	s_nop 0
	global_load_dword v110, v[22:23], off nt
	global_load_dword v111, v[24:25], off nt
	s_nop 0
	global_load_dword v112, v[26:27], off nt
	global_load_dword v113, v[28:29], off nt
	global_load_dword v114, v[30:31], off nt
	global_load_dword v115, v[32:33], off nt
	s_add_i32 s1, s1, 16
	v_add_u32_e32 v18, s1, v16
	v_add_u32_e32 v20, 2, v18
	v_add_u32_e32 v22, 4, v18
	v_add_u32_e32 v24, 6, v18
	v_ashrrev_i32_e32 v19, 31, v18
	v_add_u32_e32 v26, 8, v18
	v_add_u32_e32 v28, 10, v18
	v_add_u32_e32 v30, 12, v18
	v_add_u32_e32 v32, 14, v18
	v_ashrrev_i32_e32 v21, 31, v20
	v_ashrrev_i32_e32 v23, 31, v22
	v_ashrrev_i32_e32 v25, 31, v24
	v_lshlrev_b64 v[18:19], 12, v[18:19]
	v_ashrrev_i32_e32 v27, 31, v26
	v_ashrrev_i32_e32 v29, 31, v28
	v_ashrrev_i32_e32 v31, 31, v30
	v_ashrrev_i32_e32 v33, 31, v32
	v_lshlrev_b64 v[20:21], 12, v[20:21]
	v_lshlrev_b64 v[22:23], 12, v[22:23]
	v_lshlrev_b64 v[24:25], 12, v[24:25]
	v_lshl_add_u64 v[18:19], v[6:7], 0, v[18:19]
	v_lshlrev_b64 v[26:27], 12, v[26:27]
	v_lshlrev_b64 v[28:29], 12, v[28:29]
	v_lshlrev_b64 v[30:31], 12, v[30:31]
	v_lshlrev_b64 v[32:33], 12, v[32:33]
	v_lshl_add_u64 v[20:21], v[6:7], 0, v[20:21]
	v_lshl_add_u64 v[22:23], v[6:7], 0, v[22:23]
	v_lshl_add_u64 v[24:25], v[6:7], 0, v[24:25]
	v_lshl_add_u64 v[26:27], v[6:7], 0, v[26:27]
	v_lshl_add_u64 v[28:29], v[6:7], 0, v[28:29]
	v_lshl_add_u64 v[30:31], v[6:7], 0, v[30:31]
	v_lshl_add_u64 v[32:33], v[6:7], 0, v[32:33]
	global_load_dword v116, v[18:19], off nt
	s_nop 0
	global_load_dword v117, v[20:21], off nt
	s_nop 0
	global_load_dword v118, v[22:23], off nt
	global_load_dword v119, v[24:25], off nt
	s_nop 0
	global_load_dword v120, v[26:27], off nt
	global_load_dword v121, v[28:29], off nt
	global_load_dword v122, v[30:31], off nt
	global_load_dword v123, v[32:33], off nt
	s_add_i32 s1, s1, 16
	v_add_u32_e32 v18, s1, v16
	v_add_u32_e32 v20, 2, v18
	v_add_u32_e32 v22, 4, v18
	v_add_u32_e32 v24, 6, v18
	v_ashrrev_i32_e32 v19, 31, v18
	v_add_u32_e32 v26, 8, v18
	v_add_u32_e32 v28, 10, v18
	v_add_u32_e32 v30, 12, v18
	v_add_u32_e32 v32, 14, v18
	v_ashrrev_i32_e32 v21, 31, v20
	v_ashrrev_i32_e32 v23, 31, v22
	v_ashrrev_i32_e32 v25, 31, v24
	v_lshlrev_b64 v[18:19], 12, v[18:19]
	v_ashrrev_i32_e32 v27, 31, v26
	v_ashrrev_i32_e32 v29, 31, v28
	v_ashrrev_i32_e32 v31, 31, v30
	v_ashrrev_i32_e32 v33, 31, v32
	v_lshlrev_b64 v[20:21], 12, v[20:21]
	v_lshlrev_b64 v[22:23], 12, v[22:23]
	v_lshlrev_b64 v[24:25], 12, v[24:25]
	v_lshl_add_u64 v[18:19], v[6:7], 0, v[18:19]
	v_lshlrev_b64 v[26:27], 12, v[26:27]
	v_lshlrev_b64 v[28:29], 12, v[28:29]
	v_lshlrev_b64 v[30:31], 12, v[30:31]
	v_lshlrev_b64 v[32:33], 12, v[32:33]
	v_lshl_add_u64 v[20:21], v[6:7], 0, v[20:21]
	v_lshl_add_u64 v[22:23], v[6:7], 0, v[22:23]
	v_lshl_add_u64 v[24:25], v[6:7], 0, v[24:25]
	v_lshl_add_u64 v[26:27], v[6:7], 0, v[26:27]
	v_lshl_add_u64 v[28:29], v[6:7], 0, v[28:29]
	v_lshl_add_u64 v[30:31], v[6:7], 0, v[30:31]
	v_lshl_add_u64 v[32:33], v[6:7], 0, v[32:33]
	global_load_dword v124, v[18:19], off nt
	s_nop 0
	global_load_dword v125, v[20:21], off nt
	s_nop 0
	global_load_dword v126, v[22:23], off nt
	global_load_dword v127, v[24:25], off nt
	s_nop 0
	global_load_dword v128, v[26:27], off nt
	global_load_dword v129, v[28:29], off nt
	global_load_dword v130, v[30:31], off nt
	global_load_dword v131, v[32:33], off nt
	v_add_u32_e32 v132, 0x400, v17
	v_add_u32_e32 v133, 0x840, v17
	v_add_u32_e32 v134, 0xc40, v17
	v_add_u32_e32 v135, 0x1080, v17
	v_add_u32_e32 v136, 0x1480, v17
	v_add_u32_e32 v137, 0x18c0, v17
	v_add_u32_e32 v138, 0x1cc0, v17
	s_waitcnt vmcnt(30)
	ds_write2_b32 v17, v100, v101 offset1:66
	s_waitcnt vmcnt(28)
	ds_write2_b32 v17, v102, v103 offset0:132 offset1:198
	s_waitcnt vmcnt(26)
	ds_write2_b32 v132, v104, v105 offset0:8 offset1:74
	s_waitcnt vmcnt(24)
	ds_write2_b32 v132, v106, v107 offset0:140 offset1:206
	s_waitcnt vmcnt(22)
	ds_write2_b32 v133, v108, v109 offset1:66
	s_waitcnt vmcnt(20)
	ds_write2_b32 v133, v110, v111 offset0:132 offset1:198
	s_waitcnt vmcnt(18)
	ds_write2_b32 v134, v112, v113 offset0:8 offset1:74
	s_waitcnt vmcnt(16)
	ds_write2_b32 v134, v114, v115 offset0:140 offset1:206
	s_waitcnt vmcnt(14)
	ds_write2_b32 v135, v116, v117 offset1:66
	s_waitcnt vmcnt(12)
	ds_write2_b32 v135, v118, v119 offset0:132 offset1:198
	s_waitcnt vmcnt(10)
	ds_write2_b32 v136, v120, v121 offset0:8 offset1:74
	s_waitcnt vmcnt(8)
	ds_write2_b32 v136, v122, v123 offset0:140 offset1:206
	s_waitcnt vmcnt(6)
	ds_write2_b32 v137, v124, v125 offset1:66
	s_waitcnt vmcnt(4)
	ds_write2_b32 v137, v126, v127 offset0:132 offset1:198
	s_waitcnt vmcnt(2)
	ds_write2_b32 v138, v128, v129 offset0:8 offset1:74
	s_waitcnt vmcnt(0)
	ds_write2_b32 v138, v130, v131 offset0:140 offset1:206
	s_waitcnt lgkmcnt(0)
	ds_read2_b32 v[6:7], v9 offset0:33 offset1:41
	ds_read2_b32 v[20:21], v9 offset1:8
	ds_read2_b32 v[22:23], v9 offset0:66 offset1:74
	ds_read2_b32 v[24:25], v9 offset0:99 offset1:107
	ds_read2_b32 v[26:27], v9 offset0:132 offset1:140
	ds_read2_b32 v[28:29], v9 offset0:165 offset1:173
	ds_read2_b32 v[30:31], v9 offset0:198 offset1:206
	ds_read2_b32 v[32:33], v9 offset0:231 offset1:239
	s_waitcnt lgkmcnt(6)
	v_cvt_pk_bf16_f32 v16, v20, v6
	v_or_b32_e32 v6, s0, v8
	v_lshlrev_b32_e32 v6, 2, v6
	v_bitop3_b32 v20, s0, v14, v8 bitop3:0xc8
	v_and_or_b32 v6, v6, 16, v20
	s_ashr_i32 s7, s6, 31
	v_mul_u32_u24_e32 v36, 0x1600, v6
	v_lshl_add_u64 v[34:35], s[6:7], 1, v[4:5]
	v_ashrrev_i32_e32 v37, 31, v36
	v_or_b32_e32 v6, s0, v10
	s_waitcnt lgkmcnt(4)
	v_cvt_pk_bf16_f32 v17, v22, v24
	s_waitcnt lgkmcnt(2)
	v_cvt_pk_bf16_f32 v18, v26, v28
	s_waitcnt lgkmcnt(0)
	v_cvt_pk_bf16_f32 v19, v30, v32
	v_lshl_add_u64 v[36:37], v[34:35], 0, v[36:37]
	v_lshlrev_b32_e32 v6, 2, v6
	global_store_dwordx4 v[36:37], v[16:19], off
	v_and_b32_e32 v6, 16, v6
	s_add_i32 s8, s8, s9
	v_cvt_pk_bf16_f32 v16, v21, v7
	v_bitop3_b32 v7, s0, v15, v10 bitop3:0xc8
	v_or3_b32 v6, v7, v6, 4
	v_cvt_pk_bf16_f32 v17, v23, v25
	v_cvt_pk_bf16_f32 v18, v27, v29
	v_cvt_pk_bf16_f32 v19, v31, v33
	v_mad_i64_i32 v[6:7], s[6:7], v6, s10, v[34:35]
	ds_read2_b32 v[20:21], v9 offset0:16 offset1:24
	ds_read2_b32 v[22:23], v9 offset0:49 offset1:57
	ds_read2_b32 v[24:25], v9 offset0:82 offset1:90
	ds_read2_b32 v[26:27], v9 offset0:115 offset1:123
	ds_read2_b32 v[28:29], v9 offset0:148 offset1:156
	ds_read2_b32 v[30:31], v9 offset0:181 offset1:189
	ds_read2_b32 v[32:33], v9 offset0:214 offset1:222
	ds_read2_b32 v[36:37], v9 offset0:247 offset1:255
	global_store_dwordx4 v[6:7], v[16:19], off
	v_or_b32_e32 v6, s0, v11
	v_lshlrev_b32_e32 v6, 2, v6
	v_and_b32_e32 v6, 16, v6
	v_bitop3_b32 v7, s0, v15, v11 bitop3:0xc8
	v_or3_b32 v6, v7, v6, 8
	s_waitcnt lgkmcnt(6)
	v_cvt_pk_bf16_f32 v16, v20, v22
	s_waitcnt lgkmcnt(4)
	v_cvt_pk_bf16_f32 v17, v24, v26
	s_waitcnt lgkmcnt(2)
	v_cvt_pk_bf16_f32 v18, v28, v30
	s_waitcnt lgkmcnt(0)
	v_cvt_pk_bf16_f32 v19, v32, v36
	v_mad_i64_i32 v[6:7], s[6:7], v6, s10, v[34:35]
	global_store_dwordx4 v[6:7], v[16:19], off
	v_or_b32_e32 v6, s0, v12
	v_lshlrev_b32_e32 v6, 2, v6
	v_and_b32_e32 v6, 16, v6
	v_bitop3_b32 v7, s0, v15, v12 bitop3:0xc8
	v_or3_b32 v6, v7, v6, 12
	v_cvt_pk_bf16_f32 v16, v21, v23
	v_cvt_pk_bf16_f32 v17, v25, v27
	v_cvt_pk_bf16_f32 v18, v29, v31
	v_cvt_pk_bf16_f32 v19, v33, v37
	v_mad_i64_i32 v[6:7], s[0:1], v6, s10, v[34:35]
	global_store_dwordx4 v[6:7], v[16:19], off
	s_waitcnt lgkmcnt(0)
	s_cmpk_lt_i32 s8, 0x580
	s_cbranch_scc1 .LBB0_180
.Ldef1_begin:
	s_mov_b64 s[100:101], s[4:5]
	s_cmpk_gt_i32 s3, 0x70
	s_cselect_b32 s12, 0x70, 0
	s_cmp_lt_i32 s2, s12
	s_cbranch_scc1 .Ldef1_end
	s_sub_i32 s0, s2, s12
	s_lshl_b32 s13, s0, 3
	s_add_i32 s13, s13, s33
	s_sub_i32 s14, s3, s12
	s_cmpk_gt_u32 s13, 0x197f
	s_cbranch_scc1 .LBB0_318
	v_lshlrev_b32_e32 v2, 3, v0
	s_lshl_b32 s4, s33, 14
	v_lshrrev_b32_e32 v19, 3, v164
	v_and_b32_e32 v26, 56, v2
	s_add_i32 s0, s4, 0
	v_mul_u32_u24_e32 v2, 0x84, v26
	v_lshlrev_b32_e32 v13, 2, v19
	v_mov_b32_e32 v3, 0
	v_add3_u32 v44, s0, v2, v13
	v_lshlrev_b32_e32 v2, 1, v26
	v_lshl_add_u64 v[10:11], s[28:29], 0, v[2:3]
	s_mov_b64 s[0:1], 0x2900000
	v_lshl_add_u64 v[4:5], v[10:11], 0, s[0:1]
	s_mov_b64 s[0:1], 0x2300000
	s_lshl_b32 s15, s14, 3
	v_lshl_add_u64 v[6:7], v[10:11], 0, s[0:1]
	s_mov_b64 s[0:1], 0x1d80000
	s_add_u32 s18, s28, 0x2e00000
	v_lshl_add_u64 v[8:9], v[10:11], 0, s[0:1]
	s_mov_b64 s[0:1], 0x1280000
	s_addc_u32 s19, s29, 0
	v_lshl_add_u64 v[10:11], v[10:11], 0, s[0:1]
	s_lshl_b32 s0, s2, 3
	v_lshrrev_b32_e32 v1, 5, v164
	v_mov_b32_e32 v2, 0x6000
	s_add_i32 s0, s33, s0
	s_lshl_b32 s1, s12, 3
	v_and_b32_e32 v12, 31, v0
	v_lshl_or_b32 v49, v19, 13, v2
	v_mul_u32_u24_e32 v2, 0x84, v1
	s_sub_i32 s0, s0, s1
	v_and_b32_e32 v48, 16, v13
	v_or_b32_e32 v55, 0x80c, v13
	v_or_b32_e32 v56, 12, v13
	v_or_b32_e32 v13, s4, v2
	v_lshlrev_b32_e32 v2, 2, v12
	s_add_i32 s20, s0, 0xffffe780
	s_lshl_b32 s0, s3, 8
	s_lshl_b32 s1, s12, 8
	v_bfe_u32 v18, v0, 5, 1
	v_add3_u32 v57, v13, v2, 0
	v_lshl_add_u64 v[12:13], s[60:61], 0, v[2:3]
	s_sub_i32 s22, s0, s1
	s_lshl_b32 s0, s3, 5
	s_lshl_b32 s1, s12, 5
	v_readlane_b32 s60, v244, 0
	v_mul_u32_u24_e32 v20, 0x3000, v18
	s_sub_i32 s24, s0, s1
	v_readlane_b32 s61, v244, 1
	v_readlane_b32 s64, v244, 4
	v_readlane_b32 s65, v244, 5
	s_lshl_b32 s0, s13, 1
	s_lshl_b32 s1, s3, 4
	s_lshl_b32 s4, s12, 4
	v_mul_hi_u32_u24_e32 v21, 0x3000, v18
	v_or_b32_e32 v20, v20, v2
	s_mov_b32 s5, 0
	v_or_b32_e32 v45, 8, v19
	v_or_b32_e32 v46, 16, v19
	v_or_b32_e32 v47, 24, v19
	v_or_b32_e32 v50, 0x800, v48
	v_or_b32_e32 v51, 0x804, v48
	v_or_b32_e32 v52, 4, v48
	v_or_b32_e32 v53, 0x808, v48
	v_or_b32_e32 v54, 8, v48
	s_lshl_b32 s21, s13, 5
	v_or_b32_e32 v58, 14, v1
	s_lshl_b32 s23, s13, 2
	v_or_b32_e32 v59, 12, v1
	v_or_b32_e32 v60, 10, v1
	v_or_b32_e32 v61, 8, v1
	v_or_b32_e32 v62, 6, v1
	v_or_b32_e32 v63, 4, v1
	v_or_b32_e32 v64, 2, v1
	v_lshl_add_u64 v[14:15], s[64:65], 0, v[2:3]
	s_add_i32 s25, s0, 0x7fffd300
	s_sub_i32 s26, s1, s4
	v_lshl_add_u64 v[16:17], s[48:49], 0, v[2:3]
	v_lshl_add_u64 v[20:21], s[48:49], 0, v[20:21]
	v_lshl_add_u64 v[22:23], s[46:47], 0, v[2:3]
	s_add_i32 s27, s0, 0x7fffea00
	v_lshl_add_u64 v[24:25], s[44:45], 0, v[2:3]
	s_movk_i32 s44, 0xaff
	v_lshlrev_b32_e32 v26, 1, v26
	s_movk_i32 s45, 0x3e3
	s_movk_i32 s46, 0x2000
	s_movk_i32 s47, 0x4000
	s_mov_b32 s48, 0x1f1800
	s_movk_i32 s49, 0x7e3
	s_movk_i32 s56, 0x5000
	s_mov_b32 s57, 0xb000
	s_movk_i32 s60, 0x5800
	v_mov_b32_e32 v65, 0x3e3
	v_mov_b32_e32 v66, 0x5800
	v_mov_b32_e32 v67, 0xfffff500
	v_mov_b32_e32 v68, 0x80
	v_mov_b32_e32 v69, 0x63
	s_mov_b32 s61, s13
	v_readlane_b32 s62, v244, 2
	v_readlane_b32 s63, v244, 3
	v_readlane_b32 s66, v244, 6
	v_readlane_b32 s67, v244, 7
	s_branch .LBB0_268

.LBB0_273:
	v_lshl_add_u64 v[70:71], v[42:43], 0, s[0:1]
	v_lshl_add_u64 v[72:73], v[40:41], 0, s[0:1]
	v_lshl_add_u64 v[74:75], v[38:39], 0, s[0:1]
	v_lshl_add_u64 v[76:77], v[36:37], 0, s[0:1]
	v_lshl_add_u64 v[78:79], v[34:35], 0, s[0:1]
	v_lshl_add_u64 v[80:81], v[32:33], 0, s[0:1]
	v_lshl_add_u64 v[82:83], v[30:31], 0, s[0:1]
	v_lshl_add_u64 v[84:85], v[28:29], 0, s[0:1]
	global_load_dword v100, v[70:71], off nt
	s_nop 0
	global_load_dword v101, v[72:73], off nt
	global_load_dword v102, v[74:75], off nt
	s_nop 0
	global_load_dword v103, v[76:77], off nt
	global_load_dword v104, v[78:79], off nt
	global_load_dword v105, v[80:81], off nt
	global_load_dword v106, v[82:83], off nt
	s_nop 0
	global_load_dword v107, v[84:85], off nt
	s_add_u32 s0, s0, 0x8000
	s_addc_u32 s1, s1, 0
	v_lshl_add_u64 v[70:71], v[42:43], 0, s[0:1]
	v_lshl_add_u64 v[72:73], v[40:41], 0, s[0:1]
	v_lshl_add_u64 v[74:75], v[38:39], 0, s[0:1]
	v_lshl_add_u64 v[76:77], v[36:37], 0, s[0:1]
	v_lshl_add_u64 v[78:79], v[34:35], 0, s[0:1]
	v_lshl_add_u64 v[80:81], v[32:33], 0, s[0:1]
	v_lshl_add_u64 v[82:83], v[30:31], 0, s[0:1]
	v_lshl_add_u64 v[84:85], v[28:29], 0, s[0:1]
	global_load_dword v108, v[70:71], off nt
	s_nop 0
	global_load_dword v109, v[72:73], off nt
	global_load_dword v110, v[74:75], off nt
	s_nop 0
	global_load_dword v111, v[76:77], off nt
	global_load_dword v112, v[78:79], off nt
	global_load_dword v113, v[80:81], off nt
	global_load_dword v114, v[82:83], off nt
	s_nop 0
	global_load_dword v115, v[84:85], off nt
	s_add_u32 s0, s0, 0x8000
	s_addc_u32 s1, s1, 0
	v_lshl_add_u64 v[70:71], v[42:43], 0, s[0:1]
	v_lshl_add_u64 v[72:73], v[40:41], 0, s[0:1]
	v_lshl_add_u64 v[74:75], v[38:39], 0, s[0:1]
	v_lshl_add_u64 v[76:77], v[36:37], 0, s[0:1]
	v_lshl_add_u64 v[78:79], v[34:35], 0, s[0:1]
	v_lshl_add_u64 v[80:81], v[32:33], 0, s[0:1]
	v_lshl_add_u64 v[82:83], v[30:31], 0, s[0:1]
	v_lshl_add_u64 v[84:85], v[28:29], 0, s[0:1]
	global_load_dword v116, v[70:71], off nt
	s_nop 0
	global_load_dword v117, v[72:73], off nt
	global_load_dword v118, v[74:75], off nt
	s_nop 0
	global_load_dword v119, v[76:77], off nt
	global_load_dword v120, v[78:79], off nt
	global_load_dword v121, v[80:81], off nt
	global_load_dword v122, v[82:83], off nt
	s_nop 0
	global_load_dword v123, v[84:85], off nt
	s_add_u32 s0, s0, 0x8000
	s_addc_u32 s1, s1, 0
	v_lshl_add_u64 v[70:71], v[42:43], 0, s[0:1]
	v_lshl_add_u64 v[72:73], v[40:41], 0, s[0:1]
	v_lshl_add_u64 v[74:75], v[38:39], 0, s[0:1]
	v_lshl_add_u64 v[76:77], v[36:37], 0, s[0:1]
	v_lshl_add_u64 v[78:79], v[34:35], 0, s[0:1]
	v_lshl_add_u64 v[80:81], v[32:33], 0, s[0:1]
	v_lshl_add_u64 v[82:83], v[30:31], 0, s[0:1]
	v_lshl_add_u64 v[84:85], v[28:29], 0, s[0:1]
	global_load_dword v124, v[70:71], off nt
	s_nop 0
	global_load_dword v125, v[72:73], off nt
	global_load_dword v126, v[74:75], off nt
	s_nop 0
	global_load_dword v127, v[76:77], off nt
	global_load_dword v128, v[78:79], off nt
	global_load_dword v129, v[80:81], off nt
	global_load_dword v130, v[82:83], off nt
	s_nop 0
	global_load_dword v131, v[84:85], off nt
	v_add_u32_e32 v132, 0x400, v2
	v_add_u32_e32 v133, 0x840, v2
	v_add_u32_e32 v134, 0xc40, v2
	v_add_u32_e32 v135, 0x1080, v2
	v_add_u32_e32 v136, 0x1480, v2
	v_add_u32_e32 v137, 0x18c0, v2
	v_add_u32_e32 v138, 0x1cc0, v2
	s_waitcnt vmcnt(30)
	ds_write2_b32 v2, v100, v101 offset1:66
	s_waitcnt vmcnt(28)
	ds_write2_b32 v2, v102, v103 offset0:132 offset1:198
	s_waitcnt vmcnt(26)
	ds_write2_b32 v132, v104, v105 offset0:8 offset1:74
	s_waitcnt vmcnt(24)
	ds_write2_b32 v132, v106, v107 offset0:140 offset1:206
	s_waitcnt vmcnt(22)
	ds_write2_b32 v133, v108, v109 offset1:66
	s_waitcnt vmcnt(20)
	ds_write2_b32 v133, v110, v111 offset0:132 offset1:198
	s_waitcnt vmcnt(18)
	ds_write2_b32 v134, v112, v113 offset0:8 offset1:74
	s_waitcnt vmcnt(16)
	ds_write2_b32 v134, v114, v115 offset0:140 offset1:206
	s_waitcnt vmcnt(14)
	ds_write2_b32 v135, v116, v117 offset1:66
	s_waitcnt vmcnt(12)
	ds_write2_b32 v135, v118, v119 offset0:132 offset1:198
	s_waitcnt vmcnt(10)
	ds_write2_b32 v136, v120, v121 offset0:8 offset1:74
	s_waitcnt vmcnt(8)
	ds_write2_b32 v136, v122, v123 offset0:140 offset1:206
	s_waitcnt vmcnt(6)
	ds_write2_b32 v137, v124, v125 offset1:66
	s_waitcnt vmcnt(4)
	ds_write2_b32 v137, v126, v127 offset0:132 offset1:198
	s_waitcnt vmcnt(2)
	ds_write2_b32 v138, v128, v129 offset0:8 offset1:74
	s_waitcnt vmcnt(0)
	ds_write2_b32 v138, v130, v131 offset0:140 offset1:206
	s_add_i32 s0, s61, 0xffffe780
	s_lshr_b32 s0, s0, 7
	s_lshl_b32 s1, s61, 5
	s_and_b32 s4, s1, 0x1e0
	s_mul_hi_u32 s1, s0, 0x180000
	s_mul_i32 s0, s0, 0x180000
	s_waitcnt lgkmcnt(0)
	s_add_u32 s0, s18, s0
	s_addc_u32 s1, s19, s1
	s_lshl_b32 s8, s61, 3
	ds_read2_b32 v[32:33], v44 offset0:33 offset1:41
	ds_read2_b32 v[34:35], v44 offset1:8
	ds_read2_b32 v[36:37], v44 offset0:66 offset1:74
	ds_read2_b32 v[38:39], v44 offset0:99 offset1:107
	ds_read2_b32 v[40:41], v44 offset0:132 offset1:140
	ds_read2_b32 v[42:43], v44 offset0:165 offset1:173
	ds_read2_b32 v[70:71], v44 offset0:198 offset1:206
	ds_read2_b32 v[72:73], v44 offset0:231 offset1:239
	s_and_b32 s8, s8, 0x380
	s_add_u32 s0, s0, s8
	s_addc_u32 s1, s1, 0
	v_mov_b32_e32 v27, v3
	v_or_b32_e32 v2, s4, v19
	v_lshl_add_u64 v[74:75], s[0:1], 0, v[26:27]
	v_mul_u32_u24_e32 v2, 0xc00, v2
	s_waitcnt lgkmcnt(6)
	v_cvt_pk_bf16_f32 v28, v34, v32
	s_waitcnt lgkmcnt(4)
	v_cvt_pk_bf16_f32 v29, v36, v38
	s_waitcnt lgkmcnt(2)
	v_cvt_pk_bf16_f32 v30, v40, v42
	s_waitcnt lgkmcnt(0)
	v_cvt_pk_bf16_f32 v31, v70, v72
	v_lshl_add_u64 v[76:77], v[74:75], 0, v[2:3]
	global_store_dwordx4 v[76:77], v[28:31], off
	v_or_b32_e32 v2, s4, v45
	v_mul_u32_u24_e32 v2, 0xc00, v2
	v_cvt_pk_bf16_f32 v28, v35, v33
	v_cvt_pk_bf16_f32 v29, v37, v39
	v_cvt_pk_bf16_f32 v30, v41, v43
	v_cvt_pk_bf16_f32 v31, v71, v73
	ds_read2_b32 v[34:35], v44 offset0:16 offset1:24
	ds_read2_b32 v[36:37], v44 offset0:49 offset1:57
	ds_read2_b32 v[38:39], v44 offset0:82 offset1:90
	ds_read2_b32 v[40:41], v44 offset0:115 offset1:123
	ds_read2_b32 v[42:43], v44 offset0:148 offset1:156
	ds_read2_b32 v[70:71], v44 offset0:181 offset1:189
	ds_read2_b32 v[72:73], v44 offset0:214 offset1:222
	ds_read2_b32 v[76:77], v44 offset0:247 offset1:255
	v_lshl_add_u64 v[32:33], v[74:75], 0, v[2:3]
	v_or_b32_e32 v2, s4, v46
	v_mul_u32_u24_e32 v2, 0xc00, v2
	global_store_dwordx4 v[32:33], v[28:31], off
	v_lshl_add_u64 v[32:33], v[74:75], 0, v[2:3]
	v_or_b32_e32 v2, s4, v47
	s_waitcnt lgkmcnt(6)
	v_cvt_pk_bf16_f32 v28, v34, v36
	s_waitcnt lgkmcnt(4)
	v_cvt_pk_bf16_f32 v29, v38, v40
	s_waitcnt lgkmcnt(2)
	v_cvt_pk_bf16_f32 v30, v42, v70
	s_waitcnt lgkmcnt(0)
	v_cvt_pk_bf16_f32 v31, v72, v76
	v_mul_u32_u24_e32 v2, 0xc00, v2
	global_store_dwordx4 v[32:33], v[28:31], off
	v_lshl_add_u64 v[32:33], v[74:75], 0, v[2:3]
	s_mov_b64 s[0:1], 0
	v_cvt_pk_bf16_f32 v28, v35, v37
	v_cvt_pk_bf16_f32 v29, v39, v41
	v_cvt_pk_bf16_f32 v30, v43, v71
	v_cvt_pk_bf16_f32 v31, v73, v77
	global_store_dwordx4 v[32:33], v[28:31], off
	s_waitcnt lgkmcnt(0)

.LBB0_277:
	v_lshl_add_u64 v[70:71], v[42:43], 0, s[0:1]
	v_lshl_add_u64 v[72:73], v[40:41], 0, s[0:1]
	v_lshl_add_u64 v[74:75], v[38:39], 0, s[0:1]
	v_lshl_add_u64 v[76:77], v[36:37], 0, s[0:1]
	v_lshl_add_u64 v[78:79], v[34:35], 0, s[0:1]
	v_lshl_add_u64 v[80:81], v[32:33], 0, s[0:1]
	v_lshl_add_u64 v[82:83], v[30:31], 0, s[0:1]
	v_lshl_add_u64 v[84:85], v[28:29], 0, s[0:1]
	global_load_dword v100, v[70:71], off nt
	s_nop 0
	global_load_dword v101, v[72:73], off nt
	global_load_dword v102, v[74:75], off nt
	s_nop 0
	global_load_dword v103, v[76:77], off nt
	global_load_dword v104, v[78:79], off nt
	global_load_dword v105, v[80:81], off nt
	global_load_dword v106, v[82:83], off nt
	s_nop 0
	global_load_dword v107, v[84:85], off nt
	s_add_u32 s0, s0, 0x10000
	s_addc_u32 s1, s1, 0
	v_lshl_add_u64 v[70:71], v[42:43], 0, s[0:1]
	v_lshl_add_u64 v[72:73], v[40:41], 0, s[0:1]
	v_lshl_add_u64 v[74:75], v[38:39], 0, s[0:1]
	v_lshl_add_u64 v[76:77], v[36:37], 0, s[0:1]
	v_lshl_add_u64 v[78:79], v[34:35], 0, s[0:1]
	v_lshl_add_u64 v[80:81], v[32:33], 0, s[0:1]
	v_lshl_add_u64 v[82:83], v[30:31], 0, s[0:1]
	v_lshl_add_u64 v[84:85], v[28:29], 0, s[0:1]
	global_load_dword v108, v[70:71], off nt
	s_nop 0
	global_load_dword v109, v[72:73], off nt
	global_load_dword v110, v[74:75], off nt
	s_nop 0
	global_load_dword v111, v[76:77], off nt
	global_load_dword v112, v[78:79], off nt
	global_load_dword v113, v[80:81], off nt
	global_load_dword v114, v[82:83], off nt
	s_nop 0
	global_load_dword v115, v[84:85], off nt
	s_add_u32 s0, s0, 0x10000
	s_addc_u32 s1, s1, 0
	v_lshl_add_u64 v[70:71], v[42:43], 0, s[0:1]
	v_lshl_add_u64 v[72:73], v[40:41], 0, s[0:1]
	v_lshl_add_u64 v[74:75], v[38:39], 0, s[0:1]
	v_lshl_add_u64 v[76:77], v[36:37], 0, s[0:1]
	v_lshl_add_u64 v[78:79], v[34:35], 0, s[0:1]
	v_lshl_add_u64 v[80:81], v[32:33], 0, s[0:1]
	v_lshl_add_u64 v[82:83], v[30:31], 0, s[0:1]
	v_lshl_add_u64 v[84:85], v[28:29], 0, s[0:1]
	global_load_dword v116, v[70:71], off nt
	s_nop 0
	global_load_dword v117, v[72:73], off nt
	global_load_dword v118, v[74:75], off nt
	s_nop 0
	global_load_dword v119, v[76:77], off nt
	global_load_dword v120, v[78:79], off nt
	global_load_dword v121, v[80:81], off nt
	global_load_dword v122, v[82:83], off nt
	s_nop 0
	global_load_dword v123, v[84:85], off nt
	s_add_u32 s0, s0, 0x10000
	s_addc_u32 s1, s1, 0
	v_lshl_add_u64 v[70:71], v[42:43], 0, s[0:1]
	v_lshl_add_u64 v[72:73], v[40:41], 0, s[0:1]
	v_lshl_add_u64 v[74:75], v[38:39], 0, s[0:1]
	v_lshl_add_u64 v[76:77], v[36:37], 0, s[0:1]
	v_lshl_add_u64 v[78:79], v[34:35], 0, s[0:1]
	v_lshl_add_u64 v[80:81], v[32:33], 0, s[0:1]
	v_lshl_add_u64 v[82:83], v[30:31], 0, s[0:1]
	v_lshl_add_u64 v[84:85], v[28:29], 0, s[0:1]
	global_load_dword v124, v[70:71], off nt
	s_nop 0
	global_load_dword v125, v[72:73], off nt
	global_load_dword v126, v[74:75], off nt
	s_nop 0
	global_load_dword v127, v[76:77], off nt
	global_load_dword v128, v[78:79], off nt
	global_load_dword v129, v[80:81], off nt
	global_load_dword v130, v[82:83], off nt
	s_nop 0
	global_load_dword v131, v[84:85], off nt
	v_add_u32_e32 v132, 0x400, v2
	v_add_u32_e32 v133, 0x840, v2
	v_add_u32_e32 v134, 0xc40, v2
	v_add_u32_e32 v135, 0x1080, v2
	v_add_u32_e32 v136, 0x1480, v2
	v_add_u32_e32 v137, 0x18c0, v2
	v_add_u32_e32 v138, 0x1cc0, v2
	s_waitcnt vmcnt(30)
	ds_write2_b32 v2, v100, v101 offset1:66
	s_waitcnt vmcnt(28)
	ds_write2_b32 v2, v102, v103 offset0:132 offset1:198
	s_waitcnt vmcnt(26)
	ds_write2_b32 v132, v104, v105 offset0:8 offset1:74
	s_waitcnt vmcnt(24)
	ds_write2_b32 v132, v106, v107 offset0:140 offset1:206
	s_waitcnt vmcnt(22)
	ds_write2_b32 v133, v108, v109 offset1:66
	s_waitcnt vmcnt(20)
	ds_write2_b32 v133, v110, v111 offset0:132 offset1:198
	s_waitcnt vmcnt(18)
	ds_write2_b32 v134, v112, v113 offset0:8 offset1:74
	s_waitcnt vmcnt(16)
	ds_write2_b32 v134, v114, v115 offset0:140 offset1:206
	s_waitcnt vmcnt(14)
	ds_write2_b32 v135, v116, v117 offset1:66
	s_waitcnt vmcnt(12)
	ds_write2_b32 v135, v118, v119 offset0:132 offset1:198
	s_waitcnt vmcnt(10)
	ds_write2_b32 v136, v120, v121 offset0:8 offset1:74
	s_waitcnt vmcnt(8)
	ds_write2_b32 v136, v122, v123 offset0:140 offset1:206
	s_waitcnt vmcnt(6)
	ds_write2_b32 v137, v124, v125 offset1:66
	s_waitcnt vmcnt(4)
	ds_write2_b32 v137, v126, v127 offset0:132 offset1:198
	s_waitcnt vmcnt(2)
	ds_write2_b32 v138, v128, v129 offset0:8 offset1:74
	s_waitcnt vmcnt(0)
	ds_write2_b32 v138, v130, v131 offset0:140 offset1:206
	s_waitcnt lgkmcnt(0)
	s_lshl_b32 s0, s61, 1
	ds_read2_b32 v[32:33], v44 offset0:33 offset1:41
	ds_read2_b32 v[34:35], v44 offset1:8
	ds_read2_b32 v[36:37], v44 offset0:66 offset1:74
	ds_read2_b32 v[38:39], v44 offset0:99 offset1:107
	ds_read2_b32 v[40:41], v44 offset0:132 offset1:140
	ds_read2_b32 v[42:43], v44 offset0:165 offset1:173
	ds_read2_b32 v[70:71], v44 offset0:198 offset1:206
	ds_read2_b32 v[72:73], v44 offset0:231 offset1:239
	s_add_i32 s0, s0, 0x7fffd300
	s_and_b32 s0, s0, 0x7fffffc0
	v_lshl_or_b32 v27, s61, 5, v19
	s_lshl_b32 s4, s0, 1
	v_and_or_b32 v2, v27, s45, v48
	v_lshl_add_u64 v[74:75], v[4:5], 0, s[4:5]
	v_lshlrev_b32_e32 v2, 11, v2
	s_waitcnt lgkmcnt(6)
	v_cvt_pk_bf16_f32 v28, v34, v32
	s_waitcnt lgkmcnt(4)
	v_cvt_pk_bf16_f32 v29, v36, v38
	s_waitcnt lgkmcnt(2)
	v_cvt_pk_bf16_f32 v30, v40, v42
	s_waitcnt lgkmcnt(0)
	v_cvt_pk_bf16_f32 v31, v70, v72
	v_lshl_add_u64 v[76:77], v[74:75], 0, v[2:3]
	global_store_dwordx4 v[76:77], v[28:31], off
	v_add_co_u32_e32 v32, vcc, s46, v76
	s_nop 0
	v_cvt_pk_bf16_f32 v28, v35, v33
	v_cvt_pk_bf16_f32 v29, v37, v39
	v_cvt_pk_bf16_f32 v30, v41, v43
	v_cvt_pk_bf16_f32 v31, v71, v73
	ds_read2_b32 v[34:35], v44 offset0:49 offset1:57
	ds_read2_b32 v[36:37], v44 offset0:16 offset1:24
	ds_read2_b32 v[38:39], v44 offset0:82 offset1:90
	ds_read2_b32 v[40:41], v44 offset0:115 offset1:123
	ds_read2_b32 v[42:43], v44 offset0:148 offset1:156
	ds_read2_b32 v[70:71], v44 offset0:181 offset1:189
	ds_read2_b32 v[72:73], v44 offset0:214 offset1:222
	ds_read2_b32 v[78:79], v44 offset0:247 offset1:255
	v_addc_co_u32_e32 v33, vcc, 0, v77, vcc
	global_store_dwordx4 v[32:33], v[28:31], off
	v_add_co_u32_e32 v32, vcc, s47, v76
	v_lshlrev_b32_e32 v2, 11, v27
	s_waitcnt lgkmcnt(6)
	v_cvt_pk_bf16_f32 v28, v36, v34
	s_waitcnt lgkmcnt(4)
	v_cvt_pk_bf16_f32 v29, v38, v40
	s_waitcnt lgkmcnt(2)
	v_cvt_pk_bf16_f32 v30, v42, v70
	s_waitcnt lgkmcnt(0)
	v_cvt_pk_bf16_f32 v31, v72, v78
	v_addc_co_u32_e32 v33, vcc, 0, v77, vcc
	v_and_or_b32 v2, v2, s48, v49
	global_store_dwordx4 v[32:33], v[28:31], off
	v_lshl_add_u64 v[32:33], v[74:75], 0, v[2:3]
	s_nop 0
	v_cvt_pk_bf16_f32 v28, v37, v35
	v_cvt_pk_bf16_f32 v29, v39, v41
	v_cvt_pk_bf16_f32 v30, v43, v71
	v_cvt_pk_bf16_f32 v31, v73, v79
	global_store_dwordx4 v[32:33], v[28:31], off
	s_waitcnt lgkmcnt(0)

.LBB0_282:
	v_lshl_add_u64 v[38:39], v[36:37], 0, s[0:1]
	v_add_co_u32_e32 v74, vcc, 0x6000, v38
	global_load_dword v100, v[38:39], off nt
	s_nop 0
	v_addc_co_u32_e32 v75, vcc, 0, v39, vcc
	v_add_co_u32_e32 v76, vcc, 0xc000, v38
	global_load_dword v101, v[74:75], off nt
	s_nop 0
	v_addc_co_u32_e32 v77, vcc, 0, v39, vcc
	v_add_co_u32_e32 v38, vcc, 0x12000, v38
	v_lshl_add_u64 v[40:41], v[34:35], 0, s[0:1]
	v_lshl_add_u64 v[42:43], v[32:33], 0, s[0:1]
	v_addc_co_u32_e32 v39, vcc, 0, v39, vcc
	v_lshl_add_u64 v[70:71], v[30:31], 0, s[0:1]
	v_lshl_add_u64 v[72:73], v[28:29], 0, s[0:1]
	global_load_dword v102, v[76:77], off nt
	s_nop 0
	global_load_dword v103, v[38:39], off nt
	s_nop 0
	global_load_dword v104, v[40:41], off nt
	s_nop 0
	global_load_dword v105, v[42:43], off nt
	global_load_dword v106, v[70:71], off nt
	s_nop 0
	global_load_dword v107, v[72:73], off nt
	s_add_u32 s0, s0, 0x30000
	s_addc_u32 s1, s1, 0
	v_lshl_add_u64 v[38:39], v[36:37], 0, s[0:1]
	v_add_co_u32_e32 v74, vcc, 0x6000, v38
	global_load_dword v108, v[38:39], off nt
	s_nop 0
	v_addc_co_u32_e32 v75, vcc, 0, v39, vcc
	v_add_co_u32_e32 v76, vcc, 0xc000, v38
	global_load_dword v109, v[74:75], off nt
	s_nop 0
	v_addc_co_u32_e32 v77, vcc, 0, v39, vcc
	v_add_co_u32_e32 v38, vcc, 0x12000, v38
	v_lshl_add_u64 v[40:41], v[34:35], 0, s[0:1]
	v_lshl_add_u64 v[42:43], v[32:33], 0, s[0:1]
	v_addc_co_u32_e32 v39, vcc, 0, v39, vcc
	v_lshl_add_u64 v[70:71], v[30:31], 0, s[0:1]
	v_lshl_add_u64 v[72:73], v[28:29], 0, s[0:1]
	global_load_dword v110, v[76:77], off nt
	s_nop 0
	global_load_dword v111, v[38:39], off nt
	s_nop 0
	global_load_dword v112, v[40:41], off nt
	s_nop 0
	global_load_dword v113, v[42:43], off nt
	global_load_dword v114, v[70:71], off nt
	s_nop 0
	global_load_dword v115, v[72:73], off nt
	s_add_u32 s0, s0, 0x30000
	s_addc_u32 s1, s1, 0
	v_lshl_add_u64 v[38:39], v[36:37], 0, s[0:1]
	v_add_co_u32_e32 v74, vcc, 0x6000, v38
	global_load_dword v116, v[38:39], off nt
	s_nop 0
	v_addc_co_u32_e32 v75, vcc, 0, v39, vcc
	v_add_co_u32_e32 v76, vcc, 0xc000, v38
	global_load_dword v117, v[74:75], off nt
	s_nop 0
	v_addc_co_u32_e32 v77, vcc, 0, v39, vcc
	v_add_co_u32_e32 v38, vcc, 0x12000, v38
	v_lshl_add_u64 v[40:41], v[34:35], 0, s[0:1]
	v_lshl_add_u64 v[42:43], v[32:33], 0, s[0:1]
	v_addc_co_u32_e32 v39, vcc, 0, v39, vcc
	v_lshl_add_u64 v[70:71], v[30:31], 0, s[0:1]
	v_lshl_add_u64 v[72:73], v[28:29], 0, s[0:1]
	global_load_dword v118, v[76:77], off nt
	s_nop 0
	global_load_dword v119, v[38:39], off nt
	s_nop 0
	global_load_dword v120, v[40:41], off nt
	s_nop 0
	global_load_dword v121, v[42:43], off nt
	global_load_dword v122, v[70:71], off nt
	s_nop 0
	global_load_dword v123, v[72:73], off nt
	s_add_u32 s0, s0, 0x30000
	s_addc_u32 s1, s1, 0
	v_lshl_add_u64 v[38:39], v[36:37], 0, s[0:1]
	v_add_co_u32_e32 v74, vcc, 0x6000, v38
	global_load_dword v124, v[38:39], off nt
	s_nop 0
	v_addc_co_u32_e32 v75, vcc, 0, v39, vcc
	v_add_co_u32_e32 v76, vcc, 0xc000, v38
	global_load_dword v125, v[74:75], off nt
	s_nop 0
	v_addc_co_u32_e32 v77, vcc, 0, v39, vcc
	v_add_co_u32_e32 v38, vcc, 0x12000, v38
	v_lshl_add_u64 v[40:41], v[34:35], 0, s[0:1]
	v_lshl_add_u64 v[42:43], v[32:33], 0, s[0:1]
	v_addc_co_u32_e32 v39, vcc, 0, v39, vcc
	v_lshl_add_u64 v[70:71], v[30:31], 0, s[0:1]
	v_lshl_add_u64 v[72:73], v[28:29], 0, s[0:1]
	global_load_dword v126, v[76:77], off nt
	s_nop 0
	global_load_dword v127, v[38:39], off nt
	s_nop 0
	global_load_dword v128, v[40:41], off nt
	s_nop 0
	global_load_dword v129, v[42:43], off nt
	global_load_dword v130, v[70:71], off nt
	s_nop 0
	global_load_dword v131, v[72:73], off nt
	v_add_u32_e32 v132, 0x400, v2
	v_add_u32_e32 v133, 0x840, v2
	v_add_u32_e32 v134, 0xc40, v2
	v_add_u32_e32 v135, 0x1080, v2
	v_add_u32_e32 v136, 0x1480, v2
	v_add_u32_e32 v137, 0x18c0, v2
	v_add_u32_e32 v138, 0x1cc0, v2
	s_waitcnt vmcnt(30)
	ds_write2_b32 v2, v100, v101 offset1:66
	s_waitcnt vmcnt(28)
	ds_write2_b32 v2, v102, v103 offset0:132 offset1:198
	s_waitcnt vmcnt(26)
	ds_write2_b32 v132, v104, v105 offset0:8 offset1:74
	s_waitcnt vmcnt(24)
	ds_write2_b32 v132, v106, v107 offset0:140 offset1:206
	s_waitcnt vmcnt(22)
	ds_write2_b32 v133, v108, v109 offset1:66
	s_waitcnt vmcnt(20)
	ds_write2_b32 v133, v110, v111 offset0:132 offset1:198
	s_waitcnt vmcnt(18)
	ds_write2_b32 v134, v112, v113 offset0:8 offset1:74
	s_waitcnt vmcnt(16)
	ds_write2_b32 v134, v114, v115 offset0:140 offset1:206
	s_waitcnt vmcnt(14)
	ds_write2_b32 v135, v116, v117 offset1:66
	s_waitcnt vmcnt(12)
	ds_write2_b32 v135, v118, v119 offset0:132 offset1:198
	s_waitcnt vmcnt(10)
	ds_write2_b32 v136, v120, v121 offset0:8 offset1:74
	s_waitcnt vmcnt(8)
	ds_write2_b32 v136, v122, v123 offset0:140 offset1:206
	s_waitcnt vmcnt(6)
	ds_write2_b32 v137, v124, v125 offset1:66
	s_waitcnt vmcnt(4)
	ds_write2_b32 v137, v126, v127 offset0:132 offset1:198
	s_waitcnt vmcnt(2)
	ds_write2_b32 v138, v128, v129 offset0:8 offset1:74
	s_waitcnt vmcnt(0)
	ds_write2_b32 v138, v130, v131 offset0:140 offset1:206
	s_waitcnt lgkmcnt(0)
	ds_read2_b32 v[30:31], v44 offset1:33
	ds_read2_b32 v[32:33], v44 offset0:66 offset1:99
	ds_read2_b32 v[34:35], v44 offset0:132 offset1:165
	ds_read2_b32 v[36:37], v44 offset0:198 offset1:231
	s_and_b32 s11, 0xffff, s9
	s_and_b32 s62, 0xffff, s8
	s_cmp_gt_u32 s62, 47
	s_cselect_b64 s[8:9], -1, 0
	v_or_b32_e32 v2, s11, v19
	s_and_b64 vcc, exec, s[8:9]
	s_cbranch_vccz .LBB0_289
	s_cmp_gt_u32 s62, 63
	s_mov_b64 s[0:1], -1
	s_cbranch_scc0 .LBB0_286
	s_add_i32 s0, s11, 0xfffff800
	s_lshl_b32 s1, s11, 1
	s_and_b32 s1, s1, 0x300
	s_lshr_b32 s0, s0, 2
	v_and_b32_e32 v27, 0x63, v2
	s_and_b32 s0, s0, 0x3fffff80
	v_or3_b32 v27, v27, s1, v50
	v_add_u32_e32 v27, s0, v27
	s_mov_b64 s[0:1], 0

.LBB0_311:
	v_lshl_add_u64 v[70:71], v[42:43], 0, s[0:1]
	v_lshl_add_u64 v[72:73], v[40:41], 0, s[0:1]
	v_lshl_add_u64 v[74:75], v[38:39], 0, s[0:1]
	v_lshl_add_u64 v[76:77], v[36:37], 0, s[0:1]
	v_lshl_add_u64 v[78:79], v[34:35], 0, s[0:1]
	v_lshl_add_u64 v[80:81], v[32:33], 0, s[0:1]
	v_lshl_add_u64 v[82:83], v[30:31], 0, s[0:1]
	v_lshl_add_u64 v[84:85], v[28:29], 0, s[0:1]
	global_load_dword v100, v[70:71], off nt
	s_nop 0
	global_load_dword v101, v[72:73], off nt
	global_load_dword v102, v[74:75], off nt
	s_nop 0
	global_load_dword v103, v[76:77], off nt
	global_load_dword v104, v[78:79], off nt
	global_load_dword v105, v[80:81], off nt
	global_load_dword v106, v[82:83], off nt
	s_nop 0
	global_load_dword v107, v[84:85], off nt
	s_add_u32 s0, s0, 0x10000
	s_addc_u32 s1, s1, 0
	v_lshl_add_u64 v[70:71], v[42:43], 0, s[0:1]
	v_lshl_add_u64 v[72:73], v[40:41], 0, s[0:1]
	v_lshl_add_u64 v[74:75], v[38:39], 0, s[0:1]
	v_lshl_add_u64 v[76:77], v[36:37], 0, s[0:1]
	v_lshl_add_u64 v[78:79], v[34:35], 0, s[0:1]
	v_lshl_add_u64 v[80:81], v[32:33], 0, s[0:1]
	v_lshl_add_u64 v[82:83], v[30:31], 0, s[0:1]
	v_lshl_add_u64 v[84:85], v[28:29], 0, s[0:1]
	global_load_dword v108, v[70:71], off nt
	s_nop 0
	global_load_dword v109, v[72:73], off nt
	global_load_dword v110, v[74:75], off nt
	s_nop 0
	global_load_dword v111, v[76:77], off nt
	global_load_dword v112, v[78:79], off nt
	global_load_dword v113, v[80:81], off nt
	global_load_dword v114, v[82:83], off nt
	s_nop 0
	global_load_dword v115, v[84:85], off nt
	s_add_u32 s0, s0, 0x10000
	s_addc_u32 s1, s1, 0
	v_lshl_add_u64 v[70:71], v[42:43], 0, s[0:1]
	v_lshl_add_u64 v[72:73], v[40:41], 0, s[0:1]
	v_lshl_add_u64 v[74:75], v[38:39], 0, s[0:1]
	v_lshl_add_u64 v[76:77], v[36:37], 0, s[0:1]
	v_lshl_add_u64 v[78:79], v[34:35], 0, s[0:1]
	v_lshl_add_u64 v[80:81], v[32:33], 0, s[0:1]
	v_lshl_add_u64 v[82:83], v[30:31], 0, s[0:1]
	v_lshl_add_u64 v[84:85], v[28:29], 0, s[0:1]
	global_load_dword v116, v[70:71], off nt
	s_nop 0
	global_load_dword v117, v[72:73], off nt
	global_load_dword v118, v[74:75], off nt
	s_nop 0
	global_load_dword v119, v[76:77], off nt
	global_load_dword v120, v[78:79], off nt
	global_load_dword v121, v[80:81], off nt
	global_load_dword v122, v[82:83], off nt
	s_nop 0
	global_load_dword v123, v[84:85], off nt
	s_add_u32 s0, s0, 0x10000
	s_addc_u32 s1, s1, 0
	v_lshl_add_u64 v[70:71], v[42:43], 0, s[0:1]
	v_lshl_add_u64 v[72:73], v[40:41], 0, s[0:1]
	v_lshl_add_u64 v[74:75], v[38:39], 0, s[0:1]
	v_lshl_add_u64 v[76:77], v[36:37], 0, s[0:1]
	v_lshl_add_u64 v[78:79], v[34:35], 0, s[0:1]
	v_lshl_add_u64 v[80:81], v[32:33], 0, s[0:1]
	v_lshl_add_u64 v[82:83], v[30:31], 0, s[0:1]
	v_lshl_add_u64 v[84:85], v[28:29], 0, s[0:1]
	global_load_dword v124, v[70:71], off nt
	s_nop 0
	global_load_dword v125, v[72:73], off nt
	global_load_dword v126, v[74:75], off nt
	s_nop 0
	global_load_dword v127, v[76:77], off nt
	global_load_dword v128, v[78:79], off nt
	global_load_dword v129, v[80:81], off nt
	global_load_dword v130, v[82:83], off nt
	s_nop 0
	global_load_dword v131, v[84:85], off nt
	v_add_u32_e32 v132, 0x400, v2
	v_add_u32_e32 v133, 0x840, v2
	v_add_u32_e32 v134, 0xc40, v2
	v_add_u32_e32 v135, 0x1080, v2
	v_add_u32_e32 v136, 0x1480, v2
	v_add_u32_e32 v137, 0x18c0, v2
	v_add_u32_e32 v138, 0x1cc0, v2
	s_waitcnt vmcnt(30)
	ds_write2_b32 v2, v100, v101 offset1:66
	s_waitcnt vmcnt(28)
	ds_write2_b32 v2, v102, v103 offset0:132 offset1:198
	s_waitcnt vmcnt(26)
	ds_write2_b32 v132, v104, v105 offset0:8 offset1:74
	s_waitcnt vmcnt(24)
	ds_write2_b32 v132, v106, v107 offset0:140 offset1:206
	s_waitcnt vmcnt(22)
	ds_write2_b32 v133, v108, v109 offset1:66
	s_waitcnt vmcnt(20)
	ds_write2_b32 v133, v110, v111 offset0:132 offset1:198
	s_waitcnt vmcnt(18)
	ds_write2_b32 v134, v112, v113 offset0:8 offset1:74
	s_waitcnt vmcnt(16)
	ds_write2_b32 v134, v114, v115 offset0:140 offset1:206
	s_waitcnt vmcnt(14)
	ds_write2_b32 v135, v116, v117 offset1:66
	s_waitcnt vmcnt(12)
	ds_write2_b32 v135, v118, v119 offset0:132 offset1:198
	s_waitcnt vmcnt(10)
	ds_write2_b32 v136, v120, v121 offset0:8 offset1:74
	s_waitcnt vmcnt(8)
	ds_write2_b32 v136, v122, v123 offset0:140 offset1:206
	s_waitcnt vmcnt(6)
	ds_write2_b32 v137, v124, v125 offset1:66
	s_waitcnt vmcnt(4)
	ds_write2_b32 v137, v126, v127 offset0:132 offset1:198
	s_waitcnt vmcnt(2)
	ds_write2_b32 v138, v128, v129 offset0:8 offset1:74
	s_waitcnt vmcnt(0)
	ds_write2_b32 v138, v130, v131 offset0:140 offset1:206
	s_waitcnt lgkmcnt(0)
	s_lshl_b32 s0, s61, 1
	ds_read2_b32 v[32:33], v44 offset0:33 offset1:41
	ds_read2_b32 v[34:35], v44 offset1:8
	ds_read2_b32 v[36:37], v44 offset0:66 offset1:74
	ds_read2_b32 v[38:39], v44 offset0:99 offset1:107
	ds_read2_b32 v[40:41], v44 offset0:132 offset1:140
	ds_read2_b32 v[42:43], v44 offset0:165 offset1:173
	ds_read2_b32 v[70:71], v44 offset0:198 offset1:206
	ds_read2_b32 v[72:73], v44 offset0:231 offset1:239
	s_add_i32 s0, s0, 0x7fffea00
	s_lshl_b32 s1, s61, 5
	s_and_b32 s0, s0, 0x7fffffc0
	v_bitop3_b32 v27, s1, v65, v19 bitop3:0xc8
	s_lshl_b32 s4, s0, 1
	v_or_b32_e32 v2, v27, v48
	v_lshl_add_u64 v[74:75], v[8:9], 0, s[4:5]
	v_mul_u32_u24_e32 v2, 0x1600, v2
	s_waitcnt lgkmcnt(6)
	v_cvt_pk_bf16_f32 v28, v34, v32
	s_waitcnt lgkmcnt(4)
	v_cvt_pk_bf16_f32 v29, v36, v38
	s_waitcnt lgkmcnt(2)
	v_cvt_pk_bf16_f32 v30, v40, v42
	s_waitcnt lgkmcnt(0)
	v_cvt_pk_bf16_f32 v31, v70, v72
	v_lshl_add_u64 v[76:77], v[74:75], 0, v[2:3]
	global_store_dwordx4 v[76:77], v[28:31], off
	v_add_co_u32_e32 v32, vcc, s56, v76
	s_nop 0
	v_cvt_pk_bf16_f32 v28, v35, v33
	v_cvt_pk_bf16_f32 v29, v37, v39
	v_cvt_pk_bf16_f32 v30, v41, v43
	v_cvt_pk_bf16_f32 v31, v71, v73
	ds_read2_b32 v[34:35], v44 offset0:49 offset1:57
	ds_read2_b32 v[36:37], v44 offset0:16 offset1:24
	ds_read2_b32 v[38:39], v44 offset0:82 offset1:90
	ds_read2_b32 v[40:41], v44 offset0:115 offset1:123
	ds_read2_b32 v[42:43], v44 offset0:148 offset1:156
	ds_read2_b32 v[70:71], v44 offset0:181 offset1:189
	ds_read2_b32 v[72:73], v44 offset0:214 offset1:222
	ds_read2_b32 v[78:79], v44 offset0:247 offset1:255
	v_addc_co_u32_e32 v33, vcc, 0, v77, vcc
	global_store_dwordx4 v[32:33], v[28:31], off offset:2048
	v_add_co_u32_e32 v32, vcc, s57, v76
	v_or_b32_e32 v2, v27, v56
	s_waitcnt lgkmcnt(6)
	v_cvt_pk_bf16_f32 v28, v36, v34
	s_waitcnt lgkmcnt(4)
	v_cvt_pk_bf16_f32 v29, v38, v40
	s_waitcnt lgkmcnt(2)
	v_cvt_pk_bf16_f32 v30, v42, v70
	s_waitcnt lgkmcnt(0)
	v_cvt_pk_bf16_f32 v31, v72, v78
	v_addc_co_u32_e32 v33, vcc, 0, v77, vcc
	v_mul_u32_u24_e32 v2, 0x1600, v2
	global_store_dwordx4 v[32:33], v[28:31], off
	v_lshl_add_u64 v[32:33], v[74:75], 0, v[2:3]
	s_nop 0
	v_cvt_pk_bf16_f32 v28, v37, v35
	v_cvt_pk_bf16_f32 v29, v39, v41
	v_cvt_pk_bf16_f32 v30, v43, v71
	v_cvt_pk_bf16_f32 v31, v73, v79
	global_store_dwordx4 v[32:33], v[28:31], off
	s_waitcnt lgkmcnt(0)

.LBB0_316:
	v_lshl_add_u64 v[70:71], v[42:43], 0, s[10:11]
	v_lshl_add_u64 v[72:73], v[40:41], 0, s[10:11]
	v_lshl_add_u64 v[74:75], v[38:39], 0, s[10:11]
	v_lshl_add_u64 v[76:77], v[36:37], 0, s[10:11]
	v_lshl_add_u64 v[78:79], v[34:35], 0, s[10:11]
	v_lshl_add_u64 v[80:81], v[32:33], 0, s[10:11]
	v_lshl_add_u64 v[82:83], v[30:31], 0, s[10:11]
	v_lshl_add_u64 v[84:85], v[28:29], 0, s[10:11]
	global_load_dword v100, v[70:71], off nt
	s_nop 0
	global_load_dword v101, v[72:73], off nt
	global_load_dword v102, v[74:75], off nt
	s_nop 0
	global_load_dword v103, v[76:77], off nt
	global_load_dword v104, v[78:79], off nt
	global_load_dword v105, v[80:81], off nt
	global_load_dword v106, v[82:83], off nt
	s_nop 0
	global_load_dword v107, v[84:85], off nt
	s_add_u32 s10, s10, 0x58000
	s_addc_u32 s11, s11, 0
	v_lshl_add_u64 v[70:71], v[42:43], 0, s[10:11]
	v_lshl_add_u64 v[72:73], v[40:41], 0, s[10:11]
	v_lshl_add_u64 v[74:75], v[38:39], 0, s[10:11]
	v_lshl_add_u64 v[76:77], v[36:37], 0, s[10:11]
	v_lshl_add_u64 v[78:79], v[34:35], 0, s[10:11]
	v_lshl_add_u64 v[80:81], v[32:33], 0, s[10:11]
	v_lshl_add_u64 v[82:83], v[30:31], 0, s[10:11]
	v_lshl_add_u64 v[84:85], v[28:29], 0, s[10:11]
	global_load_dword v108, v[70:71], off nt
	s_nop 0
	global_load_dword v109, v[72:73], off nt
	global_load_dword v110, v[74:75], off nt
	s_nop 0
	global_load_dword v111, v[76:77], off nt
	global_load_dword v112, v[78:79], off nt
	global_load_dword v113, v[80:81], off nt
	global_load_dword v114, v[82:83], off nt
	s_nop 0
	global_load_dword v115, v[84:85], off nt
	s_add_u32 s10, s10, 0x58000
	s_addc_u32 s11, s11, 0
	v_lshl_add_u64 v[70:71], v[42:43], 0, s[10:11]
	v_lshl_add_u64 v[72:73], v[40:41], 0, s[10:11]
	v_lshl_add_u64 v[74:75], v[38:39], 0, s[10:11]
	v_lshl_add_u64 v[76:77], v[36:37], 0, s[10:11]
	v_lshl_add_u64 v[78:79], v[34:35], 0, s[10:11]
	v_lshl_add_u64 v[80:81], v[32:33], 0, s[10:11]
	v_lshl_add_u64 v[82:83], v[30:31], 0, s[10:11]
	v_lshl_add_u64 v[84:85], v[28:29], 0, s[10:11]
	global_load_dword v116, v[70:71], off nt
	s_nop 0
	global_load_dword v117, v[72:73], off nt
	global_load_dword v118, v[74:75], off nt
	s_nop 0
	global_load_dword v119, v[76:77], off nt
	global_load_dword v120, v[78:79], off nt
	global_load_dword v121, v[80:81], off nt
	global_load_dword v122, v[82:83], off nt
	s_nop 0
	global_load_dword v123, v[84:85], off nt
	s_add_u32 s10, s10, 0x58000
	s_addc_u32 s11, s11, 0
	v_lshl_add_u64 v[70:71], v[42:43], 0, s[10:11]
	v_lshl_add_u64 v[72:73], v[40:41], 0, s[10:11]
	v_lshl_add_u64 v[74:75], v[38:39], 0, s[10:11]
	v_lshl_add_u64 v[76:77], v[36:37], 0, s[10:11]
	v_lshl_add_u64 v[78:79], v[34:35], 0, s[10:11]
	v_lshl_add_u64 v[80:81], v[32:33], 0, s[10:11]
	v_lshl_add_u64 v[82:83], v[30:31], 0, s[10:11]
	v_lshl_add_u64 v[84:85], v[28:29], 0, s[10:11]
	global_load_dword v124, v[70:71], off nt
	s_nop 0
	global_load_dword v125, v[72:73], off nt
	global_load_dword v126, v[74:75], off nt
	s_nop 0
	global_load_dword v127, v[76:77], off nt
	global_load_dword v128, v[78:79], off nt
	global_load_dword v129, v[80:81], off nt
	global_load_dword v130, v[82:83], off nt
	s_nop 0
	global_load_dword v131, v[84:85], off nt
	v_add_u32_e32 v132, 0x400, v2
	v_add_u32_e32 v133, 0x840, v2
	v_add_u32_e32 v134, 0xc40, v2
	v_add_u32_e32 v135, 0x1080, v2
	v_add_u32_e32 v136, 0x1480, v2
	v_add_u32_e32 v137, 0x18c0, v2
	v_add_u32_e32 v138, 0x1cc0, v2
	s_waitcnt vmcnt(30)
	ds_write2_b32 v2, v100, v101 offset1:66
	s_waitcnt vmcnt(28)
	ds_write2_b32 v2, v102, v103 offset0:132 offset1:198
	s_waitcnt vmcnt(26)
	ds_write2_b32 v132, v104, v105 offset0:8 offset1:74
	s_waitcnt vmcnt(24)
	ds_write2_b32 v132, v106, v107 offset0:140 offset1:206
	s_waitcnt vmcnt(22)
	ds_write2_b32 v133, v108, v109 offset1:66
	s_waitcnt vmcnt(20)
	ds_write2_b32 v133, v110, v111 offset0:132 offset1:198
	s_waitcnt vmcnt(18)
	ds_write2_b32 v134, v112, v113 offset0:8 offset1:74
	s_waitcnt vmcnt(16)
	ds_write2_b32 v134, v114, v115 offset0:140 offset1:206
	s_waitcnt vmcnt(14)
	ds_write2_b32 v135, v116, v117 offset1:66
	s_waitcnt vmcnt(12)
	ds_write2_b32 v135, v118, v119 offset0:132 offset1:198
	s_waitcnt vmcnt(10)
	ds_write2_b32 v136, v120, v121 offset0:8 offset1:74
	s_waitcnt vmcnt(8)
	ds_write2_b32 v136, v122, v123 offset0:140 offset1:206
	s_waitcnt vmcnt(6)
	ds_write2_b32 v137, v124, v125 offset1:66
	s_waitcnt vmcnt(4)
	ds_write2_b32 v137, v126, v127 offset0:132 offset1:198
	s_waitcnt vmcnt(2)
	ds_write2_b32 v138, v128, v129 offset0:8 offset1:74
	s_waitcnt vmcnt(0)
	ds_write2_b32 v138, v130, v131 offset0:140 offset1:206
	s_waitcnt lgkmcnt(0)
	v_or_b32_e32 v2, s0, v19
	v_cmp_lt_i32_e32 vcc, s44, v2
	ds_read2_b32 v[32:33], v44 offset0:33 offset1:41
	ds_read2_b32 v[34:35], v44 offset1:8
	ds_read2_b32 v[36:37], v44 offset0:66 offset1:74
	ds_read2_b32 v[38:39], v44 offset0:99 offset1:107
	ds_read2_b32 v[40:41], v44 offset0:132 offset1:140
	ds_read2_b32 v[42:43], v44 offset0:165 offset1:173
	ds_read2_b32 v[70:71], v44 offset0:198 offset1:206
	ds_read2_b32 v[72:73], v44 offset0:231 offset1:239
	v_cndmask_b32_e32 v27, 0, v67, vcc
	s_waitcnt lgkmcnt(6)
	v_cvt_pk_bf16_f32 v28, v34, v32
	v_add_lshl_u32 v27, v27, v2, 1
	v_lshlrev_b32_e32 v2, 2, v2
	v_bitop3_b32 v34, s0, v69, v19 bitop3:0xc8
	v_and_b32_e32 v27, 0xffffff00, v27
	v_cndmask_b32_e32 v32, 0, v68, vcc
	v_and_or_b32 v2, v2, 16, v34
	v_or3_b32 v76, v2, v32, v27
	v_or_b32_e32 v2, s0, v45
	v_ashrrev_i32_e32 v77, 31, v76
	v_cmp_lt_i32_e32 vcc, s44, v2
	v_lshl_add_u64 v[74:75], s[8:9], 1, v[10:11]
	v_lshlrev_b64 v[76:77], 11, v[76:77]
	v_cndmask_b32_e32 v27, 0, v67, vcc
	s_waitcnt lgkmcnt(4)
	v_cvt_pk_bf16_f32 v29, v36, v38
	s_waitcnt lgkmcnt(2)
	v_cvt_pk_bf16_f32 v30, v40, v42
	s_waitcnt lgkmcnt(0)
	v_cvt_pk_bf16_f32 v31, v70, v72
	v_lshl_add_u64 v[76:77], v[74:75], 0, v[76:77]
	v_add_lshl_u32 v27, v27, v2, 1
	v_lshlrev_b32_e32 v2, 2, v2
	global_store_dwordx4 v[76:77], v[28:31], off
	v_cndmask_b32_e32 v32, 0, v68, vcc
	v_and_b32_e32 v2, 16, v2
	v_cvt_pk_bf16_f32 v28, v35, v33
	v_bitop3_b32 v33, s0, v69, v45 bitop3:0xc8
	v_and_b32_e32 v27, 0xffffff00, v27
	v_or3_b32 v2, v33, v2, v32
	v_or3_b32 v32, v2, v27, 4
	v_or_b32_e32 v2, s0, v46
	v_ashrrev_i32_e32 v33, 31, v32
	v_cmp_lt_i32_e32 vcc, s44, v2
	v_lshlrev_b64 v[32:33], 11, v[32:33]
	v_cvt_pk_bf16_f32 v29, v37, v39
	v_cndmask_b32_e32 v27, 0, v67, vcc
	v_cvt_pk_bf16_f32 v30, v41, v43
	v_cvt_pk_bf16_f32 v31, v71, v73
	v_lshl_add_u64 v[32:33], v[74:75], 0, v[32:33]
	v_add_lshl_u32 v27, v27, v2, 1
	v_lshlrev_b32_e32 v2, 2, v2
	ds_read2_b32 v[34:35], v44 offset0:16 offset1:24
	ds_read2_b32 v[36:37], v44 offset0:49 offset1:57
	ds_read2_b32 v[38:39], v44 offset0:82 offset1:90
	ds_read2_b32 v[40:41], v44 offset0:115 offset1:123
	ds_read2_b32 v[42:43], v44 offset0:148 offset1:156
	ds_read2_b32 v[70:71], v44 offset0:181 offset1:189
	ds_read2_b32 v[72:73], v44 offset0:214 offset1:222
	ds_read2_b32 v[76:77], v44 offset0:247 offset1:255
	global_store_dwordx4 v[32:33], v[28:31], off
	v_cndmask_b32_e32 v32, 0, v68, vcc
	v_and_b32_e32 v2, 16, v2
	v_bitop3_b32 v33, s0, v69, v46 bitop3:0xc8
	v_and_b32_e32 v27, 0xffffff00, v27
	v_or3_b32 v2, v33, v2, v32
	v_or3_b32 v32, v2, v27, 8
	v_or_b32_e32 v2, s0, v47
	v_ashrrev_i32_e32 v33, 31, v32
	v_cmp_lt_i32_e32 vcc, s44, v2
	v_lshlrev_b64 v[32:33], 11, v[32:33]
	s_waitcnt lgkmcnt(6)
	v_cvt_pk_bf16_f32 v28, v34, v36
	v_cndmask_b32_e32 v27, 0, v67, vcc
	s_waitcnt lgkmcnt(4)
	v_cvt_pk_bf16_f32 v29, v38, v40
	s_waitcnt lgkmcnt(2)
	v_cvt_pk_bf16_f32 v30, v42, v70
	s_waitcnt lgkmcnt(0)
	v_cvt_pk_bf16_f32 v31, v72, v76
	v_lshl_add_u64 v[32:33], v[74:75], 0, v[32:33]
	v_add_lshl_u32 v27, v27, v2, 1
	v_lshlrev_b32_e32 v2, 2, v2
	global_store_dwordx4 v[32:33], v[28:31], off
	v_and_b32_e32 v2, 16, v2
	v_and_b32_e32 v27, 0xffffff00, v27
	v_cndmask_b32_e32 v28, 0, v68, vcc
	v_bitop3_b32 v29, s0, v69, v47 bitop3:0xc8
	v_or3_b32 v2, v29, v2, v28
	v_or3_b32 v32, v2, v27, 12
	v_ashrrev_i32_e32 v33, 31, v32
	v_lshlrev_b64 v[32:33], 11, v[32:33]
	v_cvt_pk_bf16_f32 v28, v35, v37
	v_cvt_pk_bf16_f32 v29, v39, v41
	v_cvt_pk_bf16_f32 v30, v43, v71
	v_cvt_pk_bf16_f32 v31, v73, v77
	v_lshl_add_u64 v[32:33], v[74:75], 0, v[32:33]
	global_store_dwordx4 v[32:33], v[28:31], off
	s_waitcnt lgkmcnt(0)
	s_branch .LBB0_267

.Ldef1_end:
	s_mov_b64 s[4:5], s[100:101]

.LBB0_243:
	s_cmp_lt_i32 s30, 4
	s_cselect_b64 s[4:5], -1, 0
	s_add_u32 s42, s28, 0x4500000
	s_addc_u32 s43, s29, 0
	s_and_b64 s[6:7], s[4:5], s[0:1]
	s_andn2_b64 vcc, exec, s[6:7]
	s_cbranch_vccnz .LBB0_322
	s_cmpk_gt_i32 s2, 0xff
	v_readfirstlane_b32 s0, v0
	s_cbranch_scc1 .LBB0_264
	s_add_u32 s20, s28, 0xd00000
	s_addc_u32 s21, s29, 0
	s_ashr_i32 s23, s2, 31
	v_lshlrev_b32_e32 v1, 4, v0
	v_and_b32_e32 v2, 32, v0
	s_lshr_b32 s4, s23, 29
	v_bfe_u32 v3, v0, 2, 4
	v_bitop3_b32 v10, v1, v2, 48 bitop3:0x6c
	v_lshrrev_b32_e32 v2, 3, v0
	s_add_i32 s4, s2, s4
	v_and_or_b32 v4, v2, 48, v3
	v_or_b32_e32 v2, 64, v2
	s_movk_i32 s1, 0x70
	s_lshr_b32 s5, s0, 6
	s_ashr_i32 s8, s4, 3
	s_and_b32 s4, s4, -8
	v_and_or_b32 v2, v2, s1, v3
	s_lshr_b32 s1, s0, 8
	s_lshl_b32 s22, s5, 10
	s_sub_i32 s4, s2, s4
	s_cmp_lt_i32 s4, 0
	s_cselect_b32 s9, 33, 32
	s_mul_i32 s4, s4, s9
	s_add_i32 s4, s4, s8
	s_ashr_i32 s8, s4, 31
	s_lshr_b32 s8, s8, 27
	s_add_i32 s8, s4, s8
	s_ashr_i32 s9, s8, 5
	s_andn2_b32 s8, s8, 31
	s_sub_i32 s8, s4, s8
	s_bfe_i32 s4, s8, 0x80000
	s_bfe_u32 s4, s4, 0x3000c
	s_add_i32 s10, s8, s4
	s_bfe_i32 s4, s10, 0x80000
	s_and_b32 s10, s10, 0xf8
	s_sub_i32 s8, s8, s10
	s_lshl_b32 s9, s9, 3
	s_sext_i32_i16 s11, s4
	s_sext_i32_i8 s8, s8
	s_add_i32 s81, s9, s8
	s_ashr_i32 s8, s11, 3
	s_lshr_b32 s4, s11, 3
	s_mul_hi_i32 s9, s8, 0x160000
	s_mul_i32 s8, s8, 0x160000
	v_and_b32_e32 v11, 64, v0
	s_add_u32 s66, s20, s8
	v_or_b32_e32 v1, v10, v11
	v_mul_u32_u24_e32 v12, 0x1600, v4
	s_addc_u32 s67, s21, s9
	s_add_i32 s24, s22, 0
	v_or_b32_e32 v130, v12, v1
	s_add_i32 m0, s24, 0x10000
	v_mul_u32_u24_e32 v13, 0x1600, v2
	global_load_lds_dwordx4 v130, s[66:67]
	s_add_i32 m0, s24, 0x12000
	v_or_b32_e32 v132, v13, v1
	s_add_u32 s8, s66, 0xb0000
	global_load_lds_dwordx4 v132, s[66:67]
	s_addc_u32 s9, s67, 0
	s_add_i32 m0, s24, 0x14000
	s_mul_i32 s12, s81, 0xdc000
	global_load_lds_dwordx4 v130, s[8:9]
	s_add_i32 m0, s24, 0x16000
	s_mul_hi_i32 s10, s81, 0xdc000
	s_add_u32 s64, s40, s12
	s_addc_u32 s65, s41, s10
	s_sub_u32 s64, s64, 0x42000
	s_subb_u32 s65, s65, 0
	s_add_i32 s25, s24, 0x2000
	global_load_lds_dwordx4 v132, s[8:9]
	s_mov_b32 m0, s24
	s_add_u32 s8, s64, 0x6e000
	global_load_lds_dwordx4 v130, s[64:65]
	s_mov_b32 m0, s25
	s_addc_u32 s9, s65, 0
	s_add_i32 s26, s24, 0x4000
	global_load_lds_dwordx4 v132, s[64:65]
	s_mov_b32 m0, s26
	s_add_i32 s27, s24, 0x6000
	global_load_lds_dwordx4 v130, s[8:9]
	s_mov_b32 m0, s27
	v_mov_b32_e32 v131, 0
	global_load_lds_dwordx4 v132, s[8:9]
	v_mov_b32_e32 v133, v131
	s_cmp_eq_u32 s1, 1
	s_mov_b32 s68, 0
	v_lshl_add_u64 v[8:9], s[66:67], 0, v[130:131]
	v_lshl_add_u64 v[6:7], s[66:67], 0, v[132:133]
	v_lshl_add_u64 v[2:3], s[64:65], 0, v[130:131]
	s_cselect_b64 s[8:9], -1, 0
	s_cmp_lg_u32 s1, 1
	v_lshl_add_u64 v[4:5], s[64:65], 0, v[132:133]
	s_cbranch_scc1 .LBB0_247
	s_barrier
.LBB0_247:
	s_lshl_b32 s5, s5, 5
	s_mov_b64 s[10:11], 0x80
	s_and_b32 s5, s5, 0x60
	s_add_i32 m0, s24, 0x18000
	v_lshl_add_u64 v[8:9], v[8:9], 0, s[10:11]
	s_ashr_i32 s69, s3, 31
	s_lshl_b32 s14, s1, 13
	s_lshl_b32 s15, s5, 7
	s_waitcnt vmcnt(2)
	s_barrier
	global_load_lds_dwordx4 v[8:9], off
	v_lshl_add_u64 v[6:7], v[6:7], 0, s[10:11]
	s_add_i32 m0, s24, 0x1a000
	s_add_i32 s72, s24, 0x8000
	s_add_i32 s73, s24, 0xa000
	global_load_lds_dwordx4 v[6:7], off
	v_lshl_add_u64 v[2:3], v[2:3], 0, s[10:11]
	s_mov_b32 m0, s72
	s_add_u32 s12, s66, 0xb0080
	global_load_lds_dwordx4 v[2:3], off
	v_lshl_add_u64 v[2:3], v[4:5], 0, s[10:11]
	s_mov_b32 m0, s73
	s_addc_u32 s13, s67, 0
	global_load_lds_dwordx4 v[2:3], off
	s_add_i32 m0, s24, 0x1c000
	v_lshl_add_u64 v[2:3], s[12:13], 0, v[130:131]
	global_load_lds_dwordx4 v[2:3], off
	v_lshl_add_u64 v[2:3], s[12:13], 0, v[132:133]
	s_add_i32 m0, s24, 0x1e000
	v_lshrrev_b32_e32 v1, 1, v0
	global_load_lds_dwordx4 v[2:3], off
	v_and_b32_e32 v3, 24, v1
	s_sext_i32_i8 s82, s4
	v_lshlrev_b32_e32 v4, 1, v3
	v_lshlrev_b32_e32 v1, 6, v0
	s_movk_i32 s4, 0x3c0
	v_and_b32_e32 v2, 15, v0
	v_and_or_b32 v5, v1, s4, v4
	v_lshlrev_b32_e32 v1, 2, v0
	v_and_b32_e32 v6, 32, v1
	v_mad_u32_u24 v1, s1, 48, v2
	v_lshl_or_b32 v2, v2, 6, v4
	s_waitcnt vmcnt(6)
	s_cmpk_lt_u32 s0, 0x100
	v_bitop3_b32 v2, v2, s14, v6 bitop3:0xde
	v_bitop3_b32 v142, s15, v5, v6 bitop3:0xf6
	s_cselect_b64 s[12:13], -1, 0
	s_add_i32 s74, 0, 0x10000
	s_add_i32 s75, 0, 0x14000
	v_or_b32_e32 v143, s5, v3
	v_add3_u32 v134, v12, v10, v11
	v_mov_b32_e32 v135, v131
	v_add3_u32 v136, v13, v10, v11
	v_mov_b32_e32 v137, v131
	v_mov_b64_e32 v[138:139], 0x100
	v_mov_b64_e32 v[140:141], 0xff
	v_add_u32_e32 v144, s74, v142
	v_add_u32_e32 v145, s75, v142
	s_movk_i32 s98, 0x1000
	s_cmp_lg_u32 s12, 0
	s_cselect_b32 s98, 0x1800, s98
	v_add_u32_e32 v146, s98, v2
	s_mov_b64 s[14:15], 0x48000
	s_mov_b32 s76, 0x48000
	s_mov_b64 s[18:19], 0x50000
	s_mov_b32 s77, 0x50000
	s_mov_b64 s[56:57], 0x58000
	s_mov_b32 s78, 0x58000
	s_barrier
	s_branch .LBB0_250

.LBB0_250:
	s_add_i32 s68, s68, 1
	s_mul_i32 s0, s68, s69
	s_mul_hi_u32 s1, s68, s3
	s_add_i32 s1, s1, s0
	s_mul_i32 s0, s68, s3
	s_add_u32 s4, s0, s2
	s_addc_u32 s5, s1, s23
	v_cmp_gt_i64_e32 vcc, s[4:5], v[140:141]
	v_cmp_lt_i64_e64 s[0:1], s[4:5], v[138:139]
	s_cbranch_vccnz .LBB0_252
	s_ashr_i32 s5, s4, 31
	s_lshr_b32 s5, s5, 29
	s_add_i32 s5, s4, s5
	s_ashr_i32 s62, s5, 3
	s_and_b32 s5, s5, -8
	s_sub_i32 s4, s4, s5
	s_cmp_lt_i32 s4, 0
	s_cselect_b32 s5, 33, 32
	s_mul_i32 s4, s4, s5
	s_add_i32 s4, s4, s62
	s_ashr_i32 s5, s4, 31
	s_lshr_b32 s5, s5, 27
	s_add_i32 s5, s4, s5
	s_ashr_i32 s62, s5, 5
	s_lshl_b32 s62, s62, 3
	s_sub_i32 s63, 64, s62
	s_min_i32 s63, s63, 8
	s_abs_i32 s70, s63
	v_cvt_f32_u32_e32 v2, s70
	s_sub_i32 s79, 0, s70
	s_andn2_b32 s5, s5, 31
	s_sub_i32 s4, s4, s5
	v_rcp_iflag_f32_e32 v2, v2
	s_abs_i32 s5, s4
	s_xor_b32 s71, s4, s63
	s_ashr_i32 s71, s71, 31
	v_mul_f32_e32 v2, 0x4f7ffffe, v2
	v_cvt_u32_f32_e32 v2, v2
	s_nop 0
	v_readfirstlane_b32 s80, v2
	s_mul_i32 s79, s79, s80
	s_mul_hi_u32 s79, s80, s79
	s_add_i32 s80, s80, s79
	s_mul_hi_u32 s79, s5, s80
	s_mul_i32 s80, s79, s70
	s_sub_i32 s5, s5, s80
	s_add_i32 s83, s79, 1
	s_sub_i32 s80, s5, s70
	s_cmp_ge_u32 s5, s70
	s_cselect_b32 s79, s83, s79
	s_cselect_b32 s5, s80, s5
	s_add_i32 s80, s79, 1
	s_cmp_ge_u32 s5, s70
	s_cselect_b32 s5, s80, s79
	s_xor_b32 s5, s5, s71
	s_sub_i32 s79, s5, s71
	s_mul_i32 s5, s79, s63
	s_sub_i32 s4, s4, s5
	s_add_i32 s80, s62, s4
.LBB0_252:
	s_nop 0
	v_cndmask_b32_e64 v2, 0, 1, s[0:1]
	v_cmp_ne_u32_e64 s[4:5], 1, v2
	s_andn2_b64 vcc, exec, s[0:1]
	s_mov_b64 s[0:1], s[64:65]
	s_cbranch_vccnz .LBB0_254
	s_mul_i32 s0, s80, 0xdc000
	s_mul_hi_i32 s1, s80, 0xdc000
	s_add_u32 s0, s40, s0
	s_addc_u32 s1, s41, s1
	s_sub_u32 s0, s0, 0x42000
	s_subb_u32 s1, s1, 0

.LBB0_256:
	s_add_u32 s64, s64, 0x6e080
	s_addc_u32 s65, s65, 0
	s_add_u32 s83, s66, 0x100
	v_mov_b32_e32 v2, 0
	s_addc_u32 s84, s67, 0
	s_mov_b32 s85, -2
	v_mov_b32_e32 v3, v2
	v_mov_b32_e32 v4, v2
	v_mov_b32_e32 v5, v2
	v_mov_b32_e32 v6, v2
	v_mov_b32_e32 v7, v2
	v_mov_b32_e32 v8, v2
	v_mov_b32_e32 v9, v2
	v_mov_b32_e32 v10, v2
	v_mov_b32_e32 v11, v2
	v_mov_b32_e32 v12, v2
	v_mov_b32_e32 v13, v2
	v_mov_b32_e32 v14, v2
	v_mov_b32_e32 v15, v2
	v_mov_b32_e32 v16, v2
	v_mov_b32_e32 v17, v2
	v_mov_b32_e32 v26, v2
	v_mov_b32_e32 v27, v2
	v_mov_b32_e32 v28, v2
	v_mov_b32_e32 v29, v2
	v_mov_b32_e32 v30, v2
	v_mov_b32_e32 v31, v2
	v_mov_b32_e32 v32, v2
	v_mov_b32_e32 v33, v2
	v_mov_b32_e32 v42, v2
	v_mov_b32_e32 v43, v2
	v_mov_b32_e32 v44, v2
	v_mov_b32_e32 v45, v2
	v_mov_b32_e32 v46, v2
	v_mov_b32_e32 v47, v2
	v_mov_b32_e32 v48, v2
	v_mov_b32_e32 v49, v2
	v_mov_b32_e32 v18, v2
	v_mov_b32_e32 v19, v2
	v_mov_b32_e32 v20, v2
	v_mov_b32_e32 v21, v2
	v_mov_b32_e32 v22, v2
	v_mov_b32_e32 v23, v2
	v_mov_b32_e32 v24, v2
	v_mov_b32_e32 v25, v2
	v_mov_b32_e32 v34, v2
	v_mov_b32_e32 v35, v2
	v_mov_b32_e32 v36, v2
	v_mov_b32_e32 v37, v2
	v_mov_b32_e32 v38, v2
	v_mov_b32_e32 v39, v2
	v_mov_b32_e32 v40, v2
	v_mov_b32_e32 v41, v2
	v_mov_b32_e32 v50, v2
	v_mov_b32_e32 v51, v2
	v_mov_b32_e32 v52, v2
	v_mov_b32_e32 v53, v2
	v_mov_b32_e32 v54, v2
	v_mov_b32_e32 v55, v2
	v_mov_b32_e32 v56, v2
	v_mov_b32_e32 v57, v2
	v_mov_b32_e32 v58, v2
	v_mov_b32_e32 v59, v2
	v_mov_b32_e32 v60, v2
	v_mov_b32_e32 v61, v2
	v_mov_b32_e32 v62, v2
	v_mov_b32_e32 v63, v2
	v_mov_b32_e32 v64, v2
	v_mov_b32_e32 v65, v2
	v_mov_b32_e32 v66, v2
	v_mov_b32_e32 v67, v2
	v_mov_b32_e32 v68, v2
	v_mov_b32_e32 v69, v2
	v_mov_b32_e32 v70, v2
	v_mov_b32_e32 v71, v2
	v_mov_b32_e32 v72, v2
	v_mov_b32_e32 v73, v2
	v_mov_b32_e32 v74, v2
	v_mov_b32_e32 v75, v2
	v_mov_b32_e32 v76, v2
	v_mov_b32_e32 v77, v2
	v_mov_b32_e32 v78, v2
	v_mov_b32_e32 v79, v2
	v_mov_b32_e32 v80, v2
	v_mov_b32_e32 v81, v2
	v_mov_b32_e32 v90, v2
	v_mov_b32_e32 v91, v2
	v_mov_b32_e32 v92, v2
	v_mov_b32_e32 v93, v2
	v_mov_b32_e32 v94, v2
	v_mov_b32_e32 v95, v2
	v_mov_b32_e32 v96, v2
	v_mov_b32_e32 v97, v2
	v_mov_b32_e32 v106, v2
	v_mov_b32_e32 v107, v2
	v_mov_b32_e32 v108, v2
	v_mov_b32_e32 v109, v2
	v_mov_b32_e32 v110, v2
	v_mov_b32_e32 v111, v2
	v_mov_b32_e32 v112, v2
	v_mov_b32_e32 v113, v2
	v_mov_b32_e32 v82, v2
	v_mov_b32_e32 v83, v2
	v_mov_b32_e32 v84, v2
	v_mov_b32_e32 v85, v2
	v_mov_b32_e32 v86, v2
	v_mov_b32_e32 v87, v2
	v_mov_b32_e32 v88, v2
	v_mov_b32_e32 v89, v2
	v_mov_b32_e32 v98, v2
	v_mov_b32_e32 v99, v2
	v_mov_b32_e32 v100, v2
	v_mov_b32_e32 v101, v2
	v_mov_b32_e32 v102, v2
	v_mov_b32_e32 v103, v2
	v_mov_b32_e32 v104, v2
	v_mov_b32_e32 v105, v2
	v_mov_b32_e32 v114, v2
	v_mov_b32_e32 v115, v2
	v_mov_b32_e32 v116, v2
	v_mov_b32_e32 v117, v2
	v_mov_b32_e32 v118, v2
	v_mov_b32_e32 v119, v2
	v_mov_b32_e32 v120, v2
	v_mov_b32_e32 v121, v2
	v_mov_b32_e32 v122, v2
	v_mov_b32_e32 v123, v2
	v_mov_b32_e32 v124, v2
	v_mov_b32_e32 v125, v2
	v_mov_b32_e32 v126, v2
	v_mov_b32_e32 v127, v2
	v_mov_b32_e32 v128, v2
	v_mov_b32_e32 v129, v2
.LBB0_257:
	s_cmp_lt_u32 s24, 0x1800
	s_cbranch_scc1 .Lp3_loopA
.Lp3_loopB:
	ds_read_b128 v[148:151], v144
	ds_read_b128 v[152:155], v144 offset:1024
	ds_read_b128 v[156:159], v144 offset:2048
	ds_read_b128 v[160:163], v144 offset:3072
	ds_read_b128 v[166:169], v145
	ds_read_b128 v[170:173], v145 offset:1024
	ds_read_b128 v[174:177], v145 offset:2048
	ds_read_b128 v[178:181], v145 offset:3072
	s_add_u32 s66, s64, 0xfff92080
	s_addc_u32 s67, s65, -1
	s_cmp_eq_u32 s85, 40
	s_cselect_b32 s71, s1, s67
	s_cselect_b32 s70, s0, s66
	s_cselect_b32 s67, s63, s84
	s_cselect_b32 s66, s62, s83
	v_lshl_add_u64 v[214:215], s[64:65], 0, v[134:135]
	s_add_i32 m0, s24, 0xc000
	ds_read_b128 v[182:185], v146
	ds_read_b128 v[186:189], v146 offset:1024
	ds_read_b128 v[190:193], v146 offset:2048
	ds_read_b128 v[194:197], v146 offset:3072
	ds_read_b128 v[198:201], v146 offset:4096
	ds_read_b128 v[202:205], v146 offset:5120
	global_load_lds_dwordx4 v[214:215], off
	v_lshl_add_u64 v[214:215], s[64:65], 0, v[136:137]
	s_add_i32 m0, s24, 0xe000
	s_nop 0
	global_load_lds_dwordx4 v[214:215], off
	s_waitcnt vmcnt(8)
	s_waitcnt lgkmcnt(0)
	s_barrier
	s_setprio 1
	s_waitcnt lgkmcnt(0)
	v_mfma_f32_16x16x32_bf16 v[126:129], v[148:151], v[182:185], v[126:129]
	v_mfma_f32_16x16x32_bf16 v[122:125], v[156:159], v[182:185], v[122:125]
	v_mfma_f32_16x16x32_bf16 v[126:129], v[152:155], v[186:189], v[126:129]
	v_mfma_f32_16x16x32_bf16 v[122:125], v[160:163], v[186:189], v[122:125]
	v_mfma_f32_16x16x32_bf16 v[110:113], v[166:169], v[182:185], v[110:113]
	v_mfma_f32_16x16x32_bf16 v[106:109], v[174:177], v[182:185], v[106:109]
	v_mfma_f32_16x16x32_bf16 v[110:113], v[170:173], v[186:189], v[110:113]
	v_mfma_f32_16x16x32_bf16 v[106:109], v[178:181], v[186:189], v[106:109]
	v_mfma_f32_16x16x32_bf16 v[118:121], v[148:151], v[190:193], v[118:121]
	v_mfma_f32_16x16x32_bf16 v[114:117], v[156:159], v[190:193], v[114:117]
	v_mfma_f32_16x16x32_bf16 v[118:121], v[152:155], v[194:197], v[118:121]
	v_mfma_f32_16x16x32_bf16 v[114:117], v[160:163], v[194:197], v[114:117]
	v_mfma_f32_16x16x32_bf16 v[94:97], v[166:169], v[190:193], v[94:97]
	v_mfma_f32_16x16x32_bf16 v[90:93], v[174:177], v[190:193], v[90:93]
	v_mfma_f32_16x16x32_bf16 v[94:97], v[170:173], v[194:197], v[94:97]
	v_mfma_f32_16x16x32_bf16 v[90:93], v[178:181], v[194:197], v[90:93]
	s_cmp_eq_u32 s12, 0
	s_cbranch_scc1 .Lp3_sk0
	v_mfma_f32_16x16x32_bf16 v[102:105], v[148:151], v[198:201], v[102:105]
	v_mfma_f32_16x16x32_bf16 v[98:101], v[156:159], v[198:201], v[98:101]
	v_mfma_f32_16x16x32_bf16 v[102:105], v[152:155], v[202:205], v[102:105]
	v_mfma_f32_16x16x32_bf16 v[98:101], v[160:163], v[202:205], v[98:101]
	v_mfma_f32_16x16x32_bf16 v[78:81], v[166:169], v[198:201], v[78:81]
	v_mfma_f32_16x16x32_bf16 v[74:77], v[174:177], v[198:201], v[74:77]
	v_mfma_f32_16x16x32_bf16 v[78:81], v[170:173], v[202:205], v[78:81]
	v_mfma_f32_16x16x32_bf16 v[74:77], v[178:181], v[202:205], v[74:77]
.Lp3_sk0:
	s_setprio 0
	s_barrier
	s_add_i32 s86, s74, s22
	v_lshl_add_u64 v[214:215], s[66:67], 0, v[130:131]
	s_mov_b32 m0, s86
	ds_read_b128 v[182:185], v146 offset:16384
	ds_read_b128 v[186:189], v146 offset:17408
	ds_read_b128 v[190:193], v146 offset:18432
	ds_read_b128 v[194:197], v146 offset:19456
	ds_read_b128 v[198:201], v146 offset:20480
	ds_read_b128 v[202:205], v146 offset:21504
	global_load_lds_dwordx4 v[214:215], off
	s_add_i32 m0, s86, 0x2000
	s_add_u32 s86, s66, 0xb0000
	v_lshl_add_u64 v[216:217], s[66:67], 0, v[132:133]
	s_addc_u32 s87, s67, 0
	s_add_i32 s92, s75, s22
	global_load_lds_dwordx4 v[216:217], off
	v_lshl_add_u64 v[218:219], s[86:87], 0, v[130:131]
	s_mov_b32 m0, s92
	v_lshl_add_u64 v[220:221], s[70:71], 0, v[132:133]
	global_load_lds_dwordx4 v[218:219], off
	v_lshl_add_u64 v[218:219], s[86:87], 0, v[132:133]
	s_add_i32 m0, s92, 0x2000
	s_nop 0
	global_load_lds_dwordx4 v[218:219], off
	v_lshl_add_u64 v[218:219], s[70:71], 0, v[130:131]
	s_mov_b32 m0, s24
	s_nop 0
	global_load_lds_dwordx4 v[218:219], off
	s_mov_b32 m0, s25
	s_nop 0
	global_load_lds_dwordx4 v[220:221], off
	s_waitcnt vmcnt(8)
	s_waitcnt lgkmcnt(0)
	s_barrier
	s_setprio 1
	s_waitcnt lgkmcnt(0)
	v_mfma_f32_16x16x32_bf16 v[62:65], v[148:151], v[182:185], v[62:65]
	v_mfma_f32_16x16x32_bf16 v[58:61], v[156:159], v[182:185], v[58:61]
	v_mfma_f32_16x16x32_bf16 v[62:65], v[152:155], v[186:189], v[62:65]
	v_mfma_f32_16x16x32_bf16 v[58:61], v[160:163], v[186:189], v[58:61]
	v_mfma_f32_16x16x32_bf16 v[46:49], v[166:169], v[182:185], v[46:49]
	v_mfma_f32_16x16x32_bf16 v[42:45], v[174:177], v[182:185], v[42:45]
	v_mfma_f32_16x16x32_bf16 v[46:49], v[170:173], v[186:189], v[46:49]
	v_mfma_f32_16x16x32_bf16 v[42:45], v[178:181], v[186:189], v[42:45]
	v_mfma_f32_16x16x32_bf16 v[54:57], v[148:151], v[190:193], v[54:57]
	v_mfma_f32_16x16x32_bf16 v[50:53], v[156:159], v[190:193], v[50:53]
	v_mfma_f32_16x16x32_bf16 v[54:57], v[152:155], v[194:197], v[54:57]
	v_mfma_f32_16x16x32_bf16 v[50:53], v[160:163], v[194:197], v[50:53]
	v_mfma_f32_16x16x32_bf16 v[30:33], v[166:169], v[190:193], v[30:33]
	v_mfma_f32_16x16x32_bf16 v[26:29], v[174:177], v[190:193], v[26:29]
	v_mfma_f32_16x16x32_bf16 v[30:33], v[170:173], v[194:197], v[30:33]
	v_mfma_f32_16x16x32_bf16 v[26:29], v[178:181], v[194:197], v[26:29]
	s_cmp_eq_u32 s12, 0
	s_cbranch_scc1 .Lp3_sk1
	v_mfma_f32_16x16x32_bf16 v[38:41], v[148:151], v[198:201], v[38:41]
	v_mfma_f32_16x16x32_bf16 v[34:37], v[156:159], v[198:201], v[34:37]
	v_mfma_f32_16x16x32_bf16 v[38:41], v[152:155], v[202:205], v[38:41]
	v_mfma_f32_16x16x32_bf16 v[34:37], v[160:163], v[202:205], v[34:37]
	v_mfma_f32_16x16x32_bf16 v[14:17], v[166:169], v[198:201], v[14:17]
	v_mfma_f32_16x16x32_bf16 v[10:13], v[174:177], v[198:201], v[10:13]
	v_mfma_f32_16x16x32_bf16 v[14:17], v[170:173], v[202:205], v[14:17]
	v_mfma_f32_16x16x32_bf16 v[10:13], v[178:181], v[202:205], v[10:13]
.Lp3_sk1:
	s_setprio 0
	s_barrier
	s_add_i32 s86, 0, 0x18000
	v_add_u32_e32 v147, s86, v142
	s_add_i32 s87, 0, 0x1c000
	ds_read_b128 v[148:151], v147
	ds_read_b128 v[152:155], v147 offset:1024
	ds_read_b128 v[156:159], v147 offset:2048
	ds_read_b128 v[160:163], v147 offset:3072
	v_add_u32_e32 v147, s87, v142
	ds_read_b128 v[166:169], v147
	ds_read_b128 v[170:173], v147 offset:1024
	ds_read_b128 v[174:177], v147 offset:2048
	ds_read_b128 v[178:181], v147 offset:3072
	s_add_u32 s70, s70, 0x6e000
	s_addc_u32 s71, s71, 0
	s_mov_b32 m0, s26
	v_lshl_add_u64 v[222:223], s[70:71], 0, v[130:131]
	ds_read_b128 v[182:185], v146 offset:32768
	ds_read_b128 v[186:189], v146 offset:33792
	ds_read_b128 v[190:193], v146 offset:34816
	ds_read_b128 v[194:197], v146 offset:35840
	ds_read_b128 v[198:201], v146 offset:36864
	ds_read_b128 v[202:205], v146 offset:37888
	global_load_lds_dwordx4 v[222:223], off
	v_lshl_add_u64 v[222:223], s[70:71], 0, v[132:133]
	s_mov_b32 m0, s27
	s_nop 0
	global_load_lds_dwordx4 v[222:223], off
	s_waitcnt vmcnt(8)
	s_waitcnt lgkmcnt(0)
	s_barrier
	s_setprio 1
	s_waitcnt lgkmcnt(0)
	v_mfma_f32_16x16x32_bf16 v[126:129], v[148:151], v[182:185], v[126:129]
	v_mfma_f32_16x16x32_bf16 v[122:125], v[156:159], v[182:185], v[122:125]
	v_mfma_f32_16x16x32_bf16 v[126:129], v[152:155], v[186:189], v[126:129]
	v_mfma_f32_16x16x32_bf16 v[122:125], v[160:163], v[186:189], v[122:125]
	v_mfma_f32_16x16x32_bf16 v[110:113], v[166:169], v[182:185], v[110:113]
	v_mfma_f32_16x16x32_bf16 v[106:109], v[174:177], v[182:185], v[106:109]
	v_mfma_f32_16x16x32_bf16 v[110:113], v[170:173], v[186:189], v[110:113]
	v_mfma_f32_16x16x32_bf16 v[106:109], v[178:181], v[186:189], v[106:109]
	v_mfma_f32_16x16x32_bf16 v[118:121], v[148:151], v[190:193], v[118:121]
	v_mfma_f32_16x16x32_bf16 v[114:117], v[156:159], v[190:193], v[114:117]
	v_mfma_f32_16x16x32_bf16 v[118:121], v[152:155], v[194:197], v[118:121]
	v_mfma_f32_16x16x32_bf16 v[114:117], v[160:163], v[194:197], v[114:117]
	v_mfma_f32_16x16x32_bf16 v[94:97], v[166:169], v[190:193], v[94:97]
	v_mfma_f32_16x16x32_bf16 v[90:93], v[174:177], v[190:193], v[90:93]
	v_mfma_f32_16x16x32_bf16 v[94:97], v[170:173], v[194:197], v[94:97]
	v_mfma_f32_16x16x32_bf16 v[90:93], v[178:181], v[194:197], v[90:93]
	s_cmp_eq_u32 s12, 0
	s_cbranch_scc1 .Lp3_sk2
	v_mfma_f32_16x16x32_bf16 v[102:105], v[148:151], v[198:201], v[102:105]
	v_mfma_f32_16x16x32_bf16 v[98:101], v[156:159], v[198:201], v[98:101]
	v_mfma_f32_16x16x32_bf16 v[102:105], v[152:155], v[202:205], v[102:105]
	v_mfma_f32_16x16x32_bf16 v[98:101], v[160:163], v[202:205], v[98:101]
	v_mfma_f32_16x16x32_bf16 v[78:81], v[166:169], v[198:201], v[78:81]
	v_mfma_f32_16x16x32_bf16 v[74:77], v[174:177], v[198:201], v[74:77]
	v_mfma_f32_16x16x32_bf16 v[78:81], v[170:173], v[202:205], v[78:81]
	v_mfma_f32_16x16x32_bf16 v[74:77], v[178:181], v[202:205], v[74:77]
.Lp3_sk2:
	s_setprio 0
	s_barrier
	s_add_i32 s70, s86, s22
	v_lshl_add_u64 v[214:215], v[214:215], 0, s[10:11]
	s_mov_b32 m0, s70
	ds_read_b128 v[182:185], v146 offset:49152
	ds_read_b128 v[186:189], v146 offset:50176
	ds_read_b128 v[190:193], v146 offset:51200
	ds_read_b128 v[194:197], v146 offset:52224
	ds_read_b128 v[198:201], v146 offset:53248
	ds_read_b128 v[202:205], v146 offset:54272
	global_load_lds_dwordx4 v[214:215], off
	s_add_i32 m0, s70, 0x2000
	s_add_u32 s66, s66, 0xb0080
	v_lshl_add_u64 v[214:215], v[216:217], 0, s[10:11]
	s_addc_u32 s67, s67, 0
	s_add_i32 s70, s87, s22
	global_load_lds_dwordx4 v[214:215], off
	v_lshl_add_u64 v[214:215], s[66:67], 0, v[130:131]
	s_mov_b32 m0, s70
	s_nop 0
	global_load_lds_dwordx4 v[214:215], off
	v_lshl_add_u64 v[214:215], s[66:67], 0, v[132:133]
	s_add_i32 m0, s70, 0x2000
	s_nop 0
	global_load_lds_dwordx4 v[214:215], off
	v_lshl_add_u64 v[214:215], v[218:219], 0, s[10:11]
	s_mov_b32 m0, s72
	s_nop 0
	global_load_lds_dwordx4 v[214:215], off
	v_lshl_add_u64 v[214:215], v[220:221], 0, s[10:11]
	s_mov_b32 m0, s73
	s_nop 0
	global_load_lds_dwordx4 v[214:215], off
	s_waitcnt vmcnt(8)
	s_waitcnt lgkmcnt(0)
	s_barrier
	s_setprio 1
	s_waitcnt lgkmcnt(0)
	v_mfma_f32_16x16x32_bf16 v[62:65], v[148:151], v[182:185], v[62:65]
	v_mfma_f32_16x16x32_bf16 v[58:61], v[156:159], v[182:185], v[58:61]
	v_mfma_f32_16x16x32_bf16 v[62:65], v[152:155], v[186:189], v[62:65]
	v_mfma_f32_16x16x32_bf16 v[58:61], v[160:163], v[186:189], v[58:61]
	v_mfma_f32_16x16x32_bf16 v[46:49], v[166:169], v[182:185], v[46:49]
	v_mfma_f32_16x16x32_bf16 v[42:45], v[174:177], v[182:185], v[42:45]
	v_mfma_f32_16x16x32_bf16 v[46:49], v[170:173], v[186:189], v[46:49]
	v_mfma_f32_16x16x32_bf16 v[42:45], v[178:181], v[186:189], v[42:45]
	v_mfma_f32_16x16x32_bf16 v[54:57], v[148:151], v[190:193], v[54:57]
	v_mfma_f32_16x16x32_bf16 v[50:53], v[156:159], v[190:193], v[50:53]
	v_mfma_f32_16x16x32_bf16 v[54:57], v[152:155], v[194:197], v[54:57]
	v_mfma_f32_16x16x32_bf16 v[50:53], v[160:163], v[194:197], v[50:53]
	v_mfma_f32_16x16x32_bf16 v[30:33], v[166:169], v[190:193], v[30:33]
	v_mfma_f32_16x16x32_bf16 v[26:29], v[174:177], v[190:193], v[26:29]
	v_mfma_f32_16x16x32_bf16 v[30:33], v[170:173], v[194:197], v[30:33]
	v_mfma_f32_16x16x32_bf16 v[26:29], v[178:181], v[194:197], v[26:29]
	s_cmp_eq_u32 s12, 0
	s_cbranch_scc1 .Lp3_sk3
	v_mfma_f32_16x16x32_bf16 v[38:41], v[148:151], v[198:201], v[38:41]
	v_mfma_f32_16x16x32_bf16 v[34:37], v[156:159], v[198:201], v[34:37]
	v_mfma_f32_16x16x32_bf16 v[38:41], v[152:155], v[202:205], v[38:41]
	v_mfma_f32_16x16x32_bf16 v[34:37], v[160:163], v[202:205], v[34:37]
	v_mfma_f32_16x16x32_bf16 v[14:17], v[166:169], v[198:201], v[14:17]
	v_mfma_f32_16x16x32_bf16 v[10:13], v[174:177], v[198:201], v[10:13]
	v_mfma_f32_16x16x32_bf16 v[14:17], v[170:173], v[202:205], v[14:17]
	v_mfma_f32_16x16x32_bf16 v[10:13], v[178:181], v[202:205], v[10:13]
.Lp3_sk3:
	s_setprio 0
	s_barrier
	s_add_i32 s85, s85, 2
	s_add_u32 s64, s64, 0x100
	s_addc_u32 s65, s65, 0
	s_add_u32 s83, s83, 0x100
	s_addc_u32 s84, s84, 0
	s_cmp_gt_u32 s85, 41
	s_cbranch_scc0 .Lp3_loopB
	s_branch .Lp3_loopX
.Lp3_loopA:
	ds_read_b128 v[148:151], v144
	ds_read_b128 v[152:155], v144 offset:1024
	ds_read_b128 v[156:159], v144 offset:2048
	ds_read_b128 v[160:163], v144 offset:3072
	ds_read_b128 v[166:169], v145
	ds_read_b128 v[170:173], v145 offset:1024
	ds_read_b128 v[174:177], v145 offset:2048
	ds_read_b128 v[178:181], v145 offset:3072
	s_add_u32 s66, s64, 0xfff92080
	s_addc_u32 s67, s65, -1
	s_cmp_eq_u32 s85, 40
	s_cselect_b32 s71, s1, s67
	s_cselect_b32 s70, s0, s66
	s_cselect_b32 s67, s63, s84
	s_cselect_b32 s66, s62, s83
	v_lshl_add_u64 v[214:215], s[64:65], 0, v[134:135]
	ds_read_b128 v[182:185], v146
	ds_read_b128 v[186:189], v146 offset:1024
	ds_read_b128 v[190:193], v146 offset:2048
	ds_read_b128 v[194:197], v146 offset:3072
	ds_read_b128 v[198:201], v146 offset:4096
	ds_read_b128 v[202:205], v146 offset:5120
	v_lshl_add_u64 v[214:215], s[64:65], 0, v[136:137]
	s_add_i32 m0, s24, 0xe000
	s_nop 0
	global_load_lds_dwordx4 v[214:215], off
	s_waitcnt vmcnt(6)
	s_waitcnt lgkmcnt(0)
	s_barrier
	s_setprio 1
	s_waitcnt lgkmcnt(0)
	v_mfma_f32_16x16x32_bf16 v[126:129], v[148:151], v[182:185], v[126:129]
	v_mfma_f32_16x16x32_bf16 v[122:125], v[156:159], v[182:185], v[122:125]
	v_mfma_f32_16x16x32_bf16 v[126:129], v[152:155], v[186:189], v[126:129]
	v_mfma_f32_16x16x32_bf16 v[122:125], v[160:163], v[186:189], v[122:125]
	v_mfma_f32_16x16x32_bf16 v[110:113], v[166:169], v[182:185], v[110:113]
	v_mfma_f32_16x16x32_bf16 v[106:109], v[174:177], v[182:185], v[106:109]
	v_mfma_f32_16x16x32_bf16 v[110:113], v[170:173], v[186:189], v[110:113]
	v_mfma_f32_16x16x32_bf16 v[106:109], v[178:181], v[186:189], v[106:109]
	v_mfma_f32_16x16x32_bf16 v[118:121], v[148:151], v[190:193], v[118:121]
	v_mfma_f32_16x16x32_bf16 v[114:117], v[156:159], v[190:193], v[114:117]
	v_mfma_f32_16x16x32_bf16 v[118:121], v[152:155], v[194:197], v[118:121]
	v_mfma_f32_16x16x32_bf16 v[114:117], v[160:163], v[194:197], v[114:117]
	v_mfma_f32_16x16x32_bf16 v[94:97], v[166:169], v[190:193], v[94:97]
	v_mfma_f32_16x16x32_bf16 v[90:93], v[174:177], v[190:193], v[90:93]
	v_mfma_f32_16x16x32_bf16 v[94:97], v[170:173], v[194:197], v[94:97]
	v_mfma_f32_16x16x32_bf16 v[90:93], v[178:181], v[194:197], v[90:93]
	s_cmp_eq_u32 s12, 0
	s_cbranch_scc1 .Lp3_skA0
	v_mfma_f32_16x16x32_bf16 v[102:105], v[148:151], v[198:201], v[102:105]
	v_mfma_f32_16x16x32_bf16 v[98:101], v[156:159], v[198:201], v[98:101]
	v_mfma_f32_16x16x32_bf16 v[102:105], v[152:155], v[202:205], v[102:105]
	v_mfma_f32_16x16x32_bf16 v[98:101], v[160:163], v[202:205], v[98:101]
	v_mfma_f32_16x16x32_bf16 v[78:81], v[166:169], v[198:201], v[78:81]
	v_mfma_f32_16x16x32_bf16 v[74:77], v[174:177], v[198:201], v[74:77]
	v_mfma_f32_16x16x32_bf16 v[78:81], v[170:173], v[202:205], v[78:81]
	v_mfma_f32_16x16x32_bf16 v[74:77], v[178:181], v[202:205], v[74:77]
.Lp3_skA0:
	s_setprio 0
	s_barrier
	s_add_i32 s86, s74, s22
	v_lshl_add_u64 v[214:215], s[66:67], 0, v[130:131]
	s_mov_b32 m0, s86
	ds_read_b128 v[182:185], v146 offset:16384
	ds_read_b128 v[186:189], v146 offset:17408
	ds_read_b128 v[190:193], v146 offset:18432
	ds_read_b128 v[194:197], v146 offset:19456
	ds_read_b128 v[198:201], v146 offset:20480
	ds_read_b128 v[202:205], v146 offset:21504
	global_load_lds_dwordx4 v[214:215], off
	s_add_i32 m0, s86, 0x2000
	s_add_u32 s86, s66, 0xb0000
	v_lshl_add_u64 v[216:217], s[66:67], 0, v[132:133]
	s_addc_u32 s87, s67, 0
	s_add_i32 s92, s75, s22
	global_load_lds_dwordx4 v[216:217], off
	v_lshl_add_u64 v[218:219], s[86:87], 0, v[130:131]
	s_mov_b32 m0, s92
	v_lshl_add_u64 v[220:221], s[70:71], 0, v[132:133]
	global_load_lds_dwordx4 v[218:219], off
	v_lshl_add_u64 v[218:219], s[86:87], 0, v[132:133]
	s_add_i32 m0, s92, 0x2000
	s_nop 0
	global_load_lds_dwordx4 v[218:219], off
	v_lshl_add_u64 v[218:219], s[70:71], 0, v[130:131]
	s_nop 0
	s_mov_b32 m0, s25
	s_nop 0
	global_load_lds_dwordx4 v[220:221], off
	s_waitcnt vmcnt(6)
	s_waitcnt lgkmcnt(0)
	s_barrier
	s_setprio 1
	s_waitcnt lgkmcnt(0)
	v_mfma_f32_16x16x32_bf16 v[62:65], v[148:151], v[182:185], v[62:65]
	v_mfma_f32_16x16x32_bf16 v[58:61], v[156:159], v[182:185], v[58:61]
	v_mfma_f32_16x16x32_bf16 v[62:65], v[152:155], v[186:189], v[62:65]
	v_mfma_f32_16x16x32_bf16 v[58:61], v[160:163], v[186:189], v[58:61]
	v_mfma_f32_16x16x32_bf16 v[46:49], v[166:169], v[182:185], v[46:49]
	v_mfma_f32_16x16x32_bf16 v[42:45], v[174:177], v[182:185], v[42:45]
	v_mfma_f32_16x16x32_bf16 v[46:49], v[170:173], v[186:189], v[46:49]
	v_mfma_f32_16x16x32_bf16 v[42:45], v[178:181], v[186:189], v[42:45]
	v_mfma_f32_16x16x32_bf16 v[54:57], v[148:151], v[190:193], v[54:57]
	v_mfma_f32_16x16x32_bf16 v[50:53], v[156:159], v[190:193], v[50:53]
	v_mfma_f32_16x16x32_bf16 v[54:57], v[152:155], v[194:197], v[54:57]
	v_mfma_f32_16x16x32_bf16 v[50:53], v[160:163], v[194:197], v[50:53]
	v_mfma_f32_16x16x32_bf16 v[30:33], v[166:169], v[190:193], v[30:33]
	v_mfma_f32_16x16x32_bf16 v[26:29], v[174:177], v[190:193], v[26:29]
	v_mfma_f32_16x16x32_bf16 v[30:33], v[170:173], v[194:197], v[30:33]
	v_mfma_f32_16x16x32_bf16 v[26:29], v[178:181], v[194:197], v[26:29]
	s_cmp_eq_u32 s12, 0
	s_cbranch_scc1 .Lp3_skA1
	v_mfma_f32_16x16x32_bf16 v[38:41], v[148:151], v[198:201], v[38:41]
	v_mfma_f32_16x16x32_bf16 v[34:37], v[156:159], v[198:201], v[34:37]
	v_mfma_f32_16x16x32_bf16 v[38:41], v[152:155], v[202:205], v[38:41]
	v_mfma_f32_16x16x32_bf16 v[34:37], v[160:163], v[202:205], v[34:37]
	v_mfma_f32_16x16x32_bf16 v[14:17], v[166:169], v[198:201], v[14:17]
	v_mfma_f32_16x16x32_bf16 v[10:13], v[174:177], v[198:201], v[10:13]
	v_mfma_f32_16x16x32_bf16 v[14:17], v[170:173], v[202:205], v[14:17]
	v_mfma_f32_16x16x32_bf16 v[10:13], v[178:181], v[202:205], v[10:13]
.Lp3_skA1:
	s_setprio 0
	s_barrier
	s_add_i32 s86, 0, 0x18000
	v_add_u32_e32 v147, s86, v142
	s_add_i32 s87, 0, 0x1c000
	ds_read_b128 v[148:151], v147
	ds_read_b128 v[152:155], v147 offset:1024
	ds_read_b128 v[156:159], v147 offset:2048
	ds_read_b128 v[160:163], v147 offset:3072
	v_add_u32_e32 v147, s87, v142
	ds_read_b128 v[166:169], v147
	ds_read_b128 v[170:173], v147 offset:1024
	ds_read_b128 v[174:177], v147 offset:2048
	ds_read_b128 v[178:181], v147 offset:3072
	s_add_u32 s70, s70, 0x6e000
	s_addc_u32 s71, s71, 0
	v_lshl_add_u64 v[222:223], s[70:71], 0, v[130:131]
	ds_read_b128 v[182:185], v146 offset:32768
	ds_read_b128 v[186:189], v146 offset:33792
	ds_read_b128 v[190:193], v146 offset:34816
	ds_read_b128 v[194:197], v146 offset:35840
	ds_read_b128 v[198:201], v146 offset:36864
	ds_read_b128 v[202:205], v146 offset:37888
	v_lshl_add_u64 v[222:223], s[70:71], 0, v[132:133]
	s_mov_b32 m0, s27
	s_nop 0
	global_load_lds_dwordx4 v[222:223], off
	s_waitcnt vmcnt(6)
	s_waitcnt lgkmcnt(0)
	s_barrier
	s_setprio 1
	s_waitcnt lgkmcnt(0)
	v_mfma_f32_16x16x32_bf16 v[126:129], v[148:151], v[182:185], v[126:129]
	v_mfma_f32_16x16x32_bf16 v[122:125], v[156:159], v[182:185], v[122:125]
	v_mfma_f32_16x16x32_bf16 v[126:129], v[152:155], v[186:189], v[126:129]
	v_mfma_f32_16x16x32_bf16 v[122:125], v[160:163], v[186:189], v[122:125]
	v_mfma_f32_16x16x32_bf16 v[110:113], v[166:169], v[182:185], v[110:113]
	v_mfma_f32_16x16x32_bf16 v[106:109], v[174:177], v[182:185], v[106:109]
	v_mfma_f32_16x16x32_bf16 v[110:113], v[170:173], v[186:189], v[110:113]
	v_mfma_f32_16x16x32_bf16 v[106:109], v[178:181], v[186:189], v[106:109]
	v_mfma_f32_16x16x32_bf16 v[118:121], v[148:151], v[190:193], v[118:121]
	v_mfma_f32_16x16x32_bf16 v[114:117], v[156:159], v[190:193], v[114:117]
	v_mfma_f32_16x16x32_bf16 v[118:121], v[152:155], v[194:197], v[118:121]
	v_mfma_f32_16x16x32_bf16 v[114:117], v[160:163], v[194:197], v[114:117]
	v_mfma_f32_16x16x32_bf16 v[94:97], v[166:169], v[190:193], v[94:97]
	v_mfma_f32_16x16x32_bf16 v[90:93], v[174:177], v[190:193], v[90:93]
	v_mfma_f32_16x16x32_bf16 v[94:97], v[170:173], v[194:197], v[94:97]
	v_mfma_f32_16x16x32_bf16 v[90:93], v[178:181], v[194:197], v[90:93]
	s_cmp_eq_u32 s12, 0
	s_cbranch_scc1 .Lp3_skA2
	v_mfma_f32_16x16x32_bf16 v[102:105], v[148:151], v[198:201], v[102:105]
	v_mfma_f32_16x16x32_bf16 v[98:101], v[156:159], v[198:201], v[98:101]
	v_mfma_f32_16x16x32_bf16 v[102:105], v[152:155], v[202:205], v[102:105]
	v_mfma_f32_16x16x32_bf16 v[98:101], v[160:163], v[202:205], v[98:101]
	v_mfma_f32_16x16x32_bf16 v[78:81], v[166:169], v[198:201], v[78:81]
	v_mfma_f32_16x16x32_bf16 v[74:77], v[174:177], v[198:201], v[74:77]
	v_mfma_f32_16x16x32_bf16 v[78:81], v[170:173], v[202:205], v[78:81]
	v_mfma_f32_16x16x32_bf16 v[74:77], v[178:181], v[202:205], v[74:77]
.Lp3_skA2:
	s_setprio 0
	s_barrier
	s_add_i32 s70, s86, s22
	v_lshl_add_u64 v[214:215], v[214:215], 0, s[10:11]
	s_mov_b32 m0, s70
	ds_read_b128 v[182:185], v146 offset:49152
	ds_read_b128 v[186:189], v146 offset:50176
	ds_read_b128 v[190:193], v146 offset:51200
	ds_read_b128 v[194:197], v146 offset:52224
	ds_read_b128 v[198:201], v146 offset:53248
	ds_read_b128 v[202:205], v146 offset:54272
	global_load_lds_dwordx4 v[214:215], off
	s_add_i32 m0, s70, 0x2000
	s_add_u32 s66, s66, 0xb0080
	v_lshl_add_u64 v[214:215], v[216:217], 0, s[10:11]
	s_addc_u32 s67, s67, 0
	s_add_i32 s70, s87, s22
	global_load_lds_dwordx4 v[214:215], off
	v_lshl_add_u64 v[214:215], s[66:67], 0, v[130:131]
	s_mov_b32 m0, s70
	s_nop 0
	global_load_lds_dwordx4 v[214:215], off
	v_lshl_add_u64 v[214:215], s[66:67], 0, v[132:133]
	s_add_i32 m0, s70, 0x2000
	s_nop 0
	global_load_lds_dwordx4 v[214:215], off
	v_lshl_add_u64 v[214:215], v[218:219], 0, s[10:11]
	s_nop 0
	v_lshl_add_u64 v[214:215], v[220:221], 0, s[10:11]
	s_mov_b32 m0, s73
	s_nop 0
	global_load_lds_dwordx4 v[214:215], off
	s_waitcnt vmcnt(6)
	s_waitcnt lgkmcnt(0)
	s_barrier
	s_setprio 1
	s_waitcnt lgkmcnt(0)
	v_mfma_f32_16x16x32_bf16 v[62:65], v[148:151], v[182:185], v[62:65]
	v_mfma_f32_16x16x32_bf16 v[58:61], v[156:159], v[182:185], v[58:61]
	v_mfma_f32_16x16x32_bf16 v[62:65], v[152:155], v[186:189], v[62:65]
	v_mfma_f32_16x16x32_bf16 v[58:61], v[160:163], v[186:189], v[58:61]
	v_mfma_f32_16x16x32_bf16 v[46:49], v[166:169], v[182:185], v[46:49]
	v_mfma_f32_16x16x32_bf16 v[42:45], v[174:177], v[182:185], v[42:45]
	v_mfma_f32_16x16x32_bf16 v[46:49], v[170:173], v[186:189], v[46:49]
	v_mfma_f32_16x16x32_bf16 v[42:45], v[178:181], v[186:189], v[42:45]
	v_mfma_f32_16x16x32_bf16 v[54:57], v[148:151], v[190:193], v[54:57]
	v_mfma_f32_16x16x32_bf16 v[50:53], v[156:159], v[190:193], v[50:53]
	v_mfma_f32_16x16x32_bf16 v[54:57], v[152:155], v[194:197], v[54:57]
	v_mfma_f32_16x16x32_bf16 v[50:53], v[160:163], v[194:197], v[50:53]
	v_mfma_f32_16x16x32_bf16 v[30:33], v[166:169], v[190:193], v[30:33]
	v_mfma_f32_16x16x32_bf16 v[26:29], v[174:177], v[190:193], v[26:29]
	v_mfma_f32_16x16x32_bf16 v[30:33], v[170:173], v[194:197], v[30:33]
	v_mfma_f32_16x16x32_bf16 v[26:29], v[178:181], v[194:197], v[26:29]
	s_cmp_eq_u32 s12, 0
	s_cbranch_scc1 .Lp3_skA3
	v_mfma_f32_16x16x32_bf16 v[38:41], v[148:151], v[198:201], v[38:41]
	v_mfma_f32_16x16x32_bf16 v[34:37], v[156:159], v[198:201], v[34:37]
	v_mfma_f32_16x16x32_bf16 v[38:41], v[152:155], v[202:205], v[38:41]
	v_mfma_f32_16x16x32_bf16 v[34:37], v[160:163], v[202:205], v[34:37]
	v_mfma_f32_16x16x32_bf16 v[14:17], v[166:169], v[198:201], v[14:17]
	v_mfma_f32_16x16x32_bf16 v[10:13], v[174:177], v[198:201], v[10:13]
	v_mfma_f32_16x16x32_bf16 v[14:17], v[170:173], v[202:205], v[14:17]
	v_mfma_f32_16x16x32_bf16 v[10:13], v[178:181], v[202:205], v[10:13]
.Lp3_skA3:
	s_setprio 0
	s_barrier
	s_add_i32 s85, s85, 2
	s_add_u32 s64, s64, 0x100
	s_addc_u32 s65, s65, 0
	s_add_u32 s83, s83, 0x100
	s_addc_u32 s84, s84, 0
	s_cmp_gt_u32 s85, 41
	s_cbranch_scc0 .Lp3_loopA

.LBB0_260:
	s_mul_i32 s98, s81, 0xa0
	v_lshl_or_b32 v216, s82, 8, v143
	v_add_u32_e32 v214, s98, v1
	v_ashrrev_i32_e32 v217, 31, v216
	v_ashrrev_i32_e32 v215, 31, v214
	v_lshlrev_b64 v[216:217], 1, v[216:217]
	v_lshlrev_b64 v[218:219], 11, v[214:215]
	v_lshl_add_u64 v[218:219], s[42:43], 0, v[218:219]
	v_lshl_add_u64 v[218:219], v[218:219], 0, v[216:217]
	v_cvt_pk_bf16_f32 v166, v126, v127
	v_cvt_pk_bf16_f32 v167, v128, v129
	v_cvt_pk_bf16_f32 v168, v122, v123
	v_cvt_pk_bf16_f32 v169, v124, v125
	global_store_dwordx4 v[218:219], v[166:169], off
	v_cvt_pk_bf16_f32 v170, v110, v111
	v_cvt_pk_bf16_f32 v171, v112, v113
	v_cvt_pk_bf16_f32 v172, v106, v107
	v_cvt_pk_bf16_f32 v173, v108, v109
	global_store_dwordx4 v[218:219], v[170:173], off offset:256
	v_mov_b32_e32 v148, 0x8000
	v_mov_b32_e32 v149, 0
	v_lshl_add_u64 v[148:149], v[218:219], 0, v[148:149]
	v_cvt_pk_bf16_f32 v174, v118, v119
	v_cvt_pk_bf16_f32 v175, v120, v121
	v_cvt_pk_bf16_f32 v176, v114, v115
	v_cvt_pk_bf16_f32 v177, v116, v117
	global_store_dwordx4 v[148:149], v[174:177], off
	v_cvt_pk_bf16_f32 v178, v94, v95
	v_cvt_pk_bf16_f32 v179, v96, v97
	v_cvt_pk_bf16_f32 v180, v90, v91
	v_cvt_pk_bf16_f32 v181, v92, v93
	global_store_dwordx4 v[148:149], v[178:181], off offset:256
	v_mov_b32_e32 v150, 0x28000
	v_mov_b32_e32 v151, 0
	v_lshl_add_u64 v[150:151], v[218:219], 0, v[150:151]
	v_cvt_pk_bf16_f32 v182, v62, v63
	v_cvt_pk_bf16_f32 v183, v64, v65
	v_cvt_pk_bf16_f32 v184, v58, v59
	v_cvt_pk_bf16_f32 v185, v60, v61
	global_store_dwordx4 v[150:151], v[182:185], off
	v_cvt_pk_bf16_f32 v186, v46, v47
	v_cvt_pk_bf16_f32 v187, v48, v49
	v_cvt_pk_bf16_f32 v188, v42, v43
	v_cvt_pk_bf16_f32 v189, v44, v45
	global_store_dwordx4 v[150:151], v[186:189], off offset:256
	v_mov_b32_e32 v152, 0x30000
	v_mov_b32_e32 v153, 0
	v_lshl_add_u64 v[152:153], v[218:219], 0, v[152:153]
	v_cvt_pk_bf16_f32 v190, v54, v55
	v_cvt_pk_bf16_f32 v191, v56, v57
	v_cvt_pk_bf16_f32 v192, v50, v51
	v_cvt_pk_bf16_f32 v193, v52, v53
	global_store_dwordx4 v[152:153], v[190:193], off
	v_cvt_pk_bf16_f32 v194, v30, v31
	v_cvt_pk_bf16_f32 v195, v32, v33
	v_cvt_pk_bf16_f32 v196, v26, v27
	v_cvt_pk_bf16_f32 v197, v28, v29
	global_store_dwordx4 v[152:153], v[194:197], off offset:256
	s_cmp_eq_u32 s12, 0
	s_cbranch_scc1 .Lp3_epi_done
	v_mov_b32_e32 v154, 0x10000
	v_mov_b32_e32 v155, 0
	v_lshl_add_u64 v[154:155], v[218:219], 0, v[154:155]
	v_cvt_pk_bf16_f32 v198, v102, v103
	v_cvt_pk_bf16_f32 v199, v104, v105
	v_cvt_pk_bf16_f32 v200, v98, v99
	v_cvt_pk_bf16_f32 v201, v100, v101
	global_store_dwordx4 v[154:155], v[198:201], off
	v_cvt_pk_bf16_f32 v202, v78, v79
	v_cvt_pk_bf16_f32 v203, v80, v81
	v_cvt_pk_bf16_f32 v204, v74, v75
	v_cvt_pk_bf16_f32 v205, v76, v77
	global_store_dwordx4 v[154:155], v[202:205], off offset:256
	v_mov_b32_e32 v156, 0x38000
	v_mov_b32_e32 v157, 0
	v_lshl_add_u64 v[156:157], v[218:219], 0, v[156:157]
	v_cvt_pk_bf16_f32 v206, v38, v39
	v_cvt_pk_bf16_f32 v207, v40, v41
	v_cvt_pk_bf16_f32 v208, v34, v35
	v_cvt_pk_bf16_f32 v209, v36, v37
	global_store_dwordx4 v[156:157], v[206:209], off
	v_cvt_pk_bf16_f32 v210, v14, v15
	v_cvt_pk_bf16_f32 v211, v16, v17
	v_cvt_pk_bf16_f32 v212, v10, v11
	v_cvt_pk_bf16_f32 v213, v12, v13
	global_store_dwordx4 v[156:157], v[210:213], off offset:256

.LBB0_264:
.LBB0_322:
	s_cmp_gt_i32 s31, 4
	s_cselect_b64 s[0:1], -1, 0
	s_and_b64 s[4:5], s[6:7], s[0:1]
	s_andn2_b64 vcc, exec, s[4:5]
	s_cbranch_vccnz .LBB0_382
	s_waitcnt vmcnt(0)
	s_waitcnt vmcnt(0)
	s_barrier
	s_and_saveexec_b64 s[4:5], s[16:17]
	s_cbranch_execz .LBB0_381
	s_add_i32 s6, 0, 0x20160
	v_mov_b32_e32 v1, s6
	s_waitcnt vmcnt(0) expcnt(0) lgkmcnt(0)
	ds_read_b32 v3, v1
	s_add_i32 s6, 0, 0x20164
	v_mov_b32_e32 v1, s6
	ds_read_b32 v1, v1
	s_waitcnt lgkmcnt(1)
	v_cmp_ne_u32_e32 vcc, 0, v3
	s_cbranch_vccnz .LBB0_339
	s_load_dwordx2 s[10:11], s[94:95], 0x4
	s_add_u32 s6, s28, 0x1200
	s_addc_u32 s7, s29, 0
	s_add_u32 s8, s28, 0x1400
	s_addc_u32 s9, s29, 0
	s_waitcnt lgkmcnt(0)
	s_mul_i32 s20, s10, s3
	s_add_u32 s10, s28, 0x1500
	s_mul_i32 s20, s20, s11
	s_addc_u32 s11, s29, 0
	s_add_u32 s12, s28, 0x1600
	s_addc_u32 s13, s29, 0
	s_add_u32 s14, s28, 0x1700
	s_addc_u32 s15, s29, 0
	s_add_u32 s18, s28, 0x1800
	s_addc_u32 s19, s29, 0
	s_add_u32 s24, s28, 0x1900
	s_addc_u32 s25, s29, 0
	s_add_u32 s44, s28, 0x1a00
	s_addc_u32 s45, s29, 0
	s_add_u32 s46, s28, 0x1b00
	s_addc_u32 s47, s29, 0
	s_add_u32 s48, s28, 0x1c00
	s_addc_u32 s49, s29, 0
	s_add_u32 s56, s28, 0x1d00
	s_addc_u32 s57, s29, 0
	s_add_u32 s58, s28, 0x1e00
	s_addc_u32 s59, s29, 0
	s_add_u32 s60, s28, 0x1f00
	s_addc_u32 s61, s29, 0
	s_add_u32 s62, s28, 0x2000
	s_addc_u32 s63, s29, 0
	s_add_u32 s64, s28, 0x2100
	s_addc_u32 s65, s29, 0
	s_add_u32 s66, s28, 0x2200
	s_addc_u32 s67, s29, 0
	s_add_u32 s70, s28, 0x2300
	s_addc_u32 s71, s29, 0
	s_mov_b32 s21, 1
	v_mov_b32_e32 v17, 0
	s_branch .LBB0_327

.Ld1b_begin:
	s_mov_b64 s[98:99], s[4:5]
	s_sub_u32 s100, s94, 0xb8
	s_subb_u32 s101, s95, 0
	s_load_dwordx4 s[44:47], s[100:101], 0x60
	s_load_dwordx2 s[48:49], s[100:101], 0x70
	s_load_dwordx2 s[58:59], s[100:101], 0x18
	s_load_dwordx2 s[60:61], s[100:101], 0x20
	s_waitcnt lgkmcnt(0)
	s_cmpk_gt_i32 s3, 0xa0
	s_cselect_b32 s12, 0xa0, 0
	s_cmp_lt_i32 s2, s12
	s_cbranch_scc1 .Ld1b_end
	s_sub_i32 s0, s2, s12
	s_lshl_b32 s13, s0, 3
	s_add_i32 s13, s13, s33
	s_sub_i32 s14, s3, s12
	s_cmpk_gt_u32 s13, 0x197f
	s_cbranch_scc1 .Ld1b_end
	v_lshlrev_b32_e32 v2, 3, v0
	s_lshl_b32 s4, s33, 14
	v_lshrrev_b32_e32 v19, 3, v164
	v_and_b32_e32 v26, 56, v2
	s_add_i32 s0, s4, 0
	v_mul_u32_u24_e32 v2, 0x84, v26
	v_lshlrev_b32_e32 v13, 2, v19
	v_mov_b32_e32 v3, 0
	v_add3_u32 v44, s0, v2, v13
	v_lshlrev_b32_e32 v2, 1, v26
	v_lshl_add_u64 v[10:11], s[28:29], 0, v[2:3]
	s_mov_b64 s[0:1], 0x2900000
	v_lshl_add_u64 v[4:5], v[10:11], 0, s[0:1]
	s_mov_b64 s[0:1], 0x2300000
	s_lshl_b32 s15, s14, 3
	v_lshl_add_u64 v[6:7], v[10:11], 0, s[0:1]
	s_mov_b64 s[0:1], 0x1d80000
	s_add_u32 s18, s28, 0x2e00000
	v_lshl_add_u64 v[8:9], v[10:11], 0, s[0:1]
	s_mov_b64 s[0:1], 0x1280000
	s_addc_u32 s19, s29, 0
	v_lshl_add_u64 v[10:11], v[10:11], 0, s[0:1]
	s_lshl_b32 s0, s2, 3
	v_lshrrev_b32_e32 v1, 5, v164
	v_mov_b32_e32 v2, 0x6000
	s_add_i32 s0, s33, s0
	s_lshl_b32 s1, s12, 3
	v_and_b32_e32 v12, 31, v0
	v_lshl_or_b32 v49, v19, 13, v2
	v_mul_u32_u24_e32 v2, 0x84, v1
	s_sub_i32 s0, s0, s1
	v_and_b32_e32 v48, 16, v13
	v_or_b32_e32 v55, 0x80c, v13
	v_or_b32_e32 v56, 12, v13
	v_or_b32_e32 v13, s4, v2
	v_lshlrev_b32_e32 v2, 2, v12
	s_add_i32 s20, s0, 0xffffe780
	s_lshl_b32 s0, s3, 8
	s_lshl_b32 s1, s12, 8
	v_bfe_u32 v18, v0, 5, 1
	v_add3_u32 v57, v13, v2, 0
	v_lshl_add_u64 v[12:13], s[60:61], 0, v[2:3]
	s_sub_i32 s22, s0, s1
	s_lshl_b32 s0, s3, 5
	s_lshl_b32 s1, s12, 5
	v_readlane_b32 s60, v244, 0
	v_mul_u32_u24_e32 v20, 0x3000, v18
	s_sub_i32 s24, s0, s1
	v_readlane_b32 s61, v244, 1
	v_readlane_b32 s64, v244, 4
	v_readlane_b32 s65, v244, 5
	s_lshl_b32 s0, s13, 1
	s_lshl_b32 s1, s3, 4
	s_lshl_b32 s4, s12, 4
	v_mul_hi_u32_u24_e32 v21, 0x3000, v18
	v_or_b32_e32 v20, v20, v2
	s_mov_b32 s5, 0
	v_or_b32_e32 v45, 8, v19
	v_or_b32_e32 v46, 16, v19
	v_or_b32_e32 v47, 24, v19
	v_or_b32_e32 v50, 0x800, v48
	v_or_b32_e32 v51, 0x804, v48
	v_or_b32_e32 v52, 4, v48
	v_or_b32_e32 v53, 0x808, v48
	v_or_b32_e32 v54, 8, v48
	s_lshl_b32 s21, s13, 5
	v_or_b32_e32 v58, 14, v1
	s_lshl_b32 s23, s13, 2
	v_or_b32_e32 v59, 12, v1
	v_or_b32_e32 v60, 10, v1
	v_or_b32_e32 v61, 8, v1
	v_or_b32_e32 v62, 6, v1
	v_or_b32_e32 v63, 4, v1
	v_or_b32_e32 v64, 2, v1
	v_lshl_add_u64 v[14:15], s[64:65], 0, v[2:3]
	s_add_i32 s25, s0, 0x7fffd300
	s_sub_i32 s26, s1, s4
	v_lshl_add_u64 v[16:17], s[48:49], 0, v[2:3]
	v_lshl_add_u64 v[20:21], s[48:49], 0, v[20:21]
	v_lshl_add_u64 v[22:23], s[46:47], 0, v[2:3]
	s_add_i32 s27, s0, 0x7fffea00
	v_lshl_add_u64 v[24:25], s[44:45], 0, v[2:3]
	s_movk_i32 s44, 0xaff
	v_lshlrev_b32_e32 v26, 1, v26
	s_movk_i32 s45, 0x3e3
	s_movk_i32 s46, 0x2000
	s_movk_i32 s47, 0x4000
	s_mov_b32 s48, 0x1f1800
	s_movk_i32 s49, 0x7e3
	s_movk_i32 s56, 0x5000
	s_mov_b32 s57, 0xb000
	s_movk_i32 s60, 0x5800
	v_mov_b32_e32 v65, 0x3e3
	v_mov_b32_e32 v66, 0x5800
	v_mov_b32_e32 v67, 0xfffff500
	v_mov_b32_e32 v68, 0x80
	v_mov_b32_e32 v69, 0x63
	s_mov_b32 s61, s13
	v_readlane_b32 s62, v244, 2
	v_readlane_b32 s63, v244, 3
	v_readlane_b32 s66, v244, 6
	v_readlane_b32 s67, v244, 7
	s_branch .Ld1b_268

.Ld1b_268:
	s_cmpk_gt_i32 s61, 0xaff
	s_mov_b64 s[0:1], -1
	s_cbranch_scc0 .Ld1b_314
	s_branch .Ld1b_end
	s_lshl_b32 s0, s21, 2
	s_and_b32 s10, s0, 0xf80
	s_cmpk_gt_u32 s61, 0x107f
	s_mov_b64 s[0:1], -1
	s_cbranch_scc0 .Ld1b_309
	s_cmpk_gt_u32 s61, 0x167f
	s_cbranch_scc0 .Ld1b_280
	s_cmpk_gt_u32 s61, 0x187f
	s_cbranch_scc0 .Ld1b_275
	s_lshr_b32 s8, s21, 5
	s_lshr_b32 s4, s20, 7
	s_lshl_b64 s[0:1], s[4:5], 20
	s_and_b32 s4, s8, 15
	s_lshl_b32 s4, s4, 7
	s_or_b32 s0, s0, s4
	s_and_b32 s4, s23, 0x1c0
	v_or_b32_e32 v2, s4, v58
	v_lshl_or_b32 v42, v2, 11, s0
	v_mov_b32_e32 v43, s1
	v_or_b32_e32 v2, s4, v59
	v_lshl_add_u64 v[28:29], v[12:13], 0, v[42:43]
	v_lshl_or_b32 v42, v2, 11, s0
	v_or_b32_e32 v2, s4, v60
	v_lshl_add_u64 v[30:31], v[12:13], 0, v[42:43]
	v_lshl_or_b32 v42, v2, 11, s0
	v_or_b32_e32 v2, s4, v61
	v_lshl_add_u64 v[32:33], v[12:13], 0, v[42:43]
	v_lshl_or_b32 v42, v2, 11, s0
	v_or_b32_e32 v2, s4, v62
	v_lshl_add_u64 v[34:35], v[12:13], 0, v[42:43]
	v_lshl_or_b32 v42, v2, 11, s0
	v_or_b32_e32 v2, s4, v63
	v_lshl_add_u64 v[36:37], v[12:13], 0, v[42:43]
	v_lshl_or_b32 v42, v2, 11, s0
	v_or_b32_e32 v2, s4, v64
	v_lshl_add_u64 v[38:39], v[12:13], 0, v[42:43]
	v_lshl_or_b32 v42, v2, 11, s0
	v_or_b32_e32 v2, s4, v1
	v_lshl_add_u64 v[40:41], v[12:13], 0, v[42:43]
	v_lshl_or_b32 v42, v2, 11, s0
	v_lshl_add_u64 v[42:43], v[12:13], 0, v[42:43]
	s_mov_b64 s[0:1], 0
	v_mov_b32_e32 v2, v57

.Ld1b_end:
	s_mov_b64 s[4:5], s[98:99]

.Ld1c_begin:
	s_mov_b64 s[98:99], s[4:5]
	s_sub_u32 s100, s94, 0xb8
	s_subb_u32 s101, s95, 0
	s_load_dwordx4 s[44:47], s[100:101], 0x60
	s_load_dwordx2 s[48:49], s[100:101], 0x70
	s_load_dwordx2 s[58:59], s[100:101], 0x18
	s_load_dwordx2 s[60:61], s[100:101], 0x20
	s_waitcnt lgkmcnt(0)
	s_cmpk_gt_i32 s3, 0x70
	s_cselect_b32 s12, 0x70, 0
	s_cmp_lt_i32 s2, s12
	s_cbranch_scc1 .Ld1c_end
	s_sub_i32 s0, s2, s12
	s_lshl_b32 s13, s0, 3
	s_add_i32 s13, s13, s33
	s_sub_i32 s14, s3, s12
	s_cmpk_gt_u32 s13, 0x197f
	s_cbranch_scc1 .Ld1c_end
	v_lshlrev_b32_e32 v2, 3, v0
	s_lshl_b32 s4, s33, 14
	v_lshrrev_b32_e32 v19, 3, v164
	v_and_b32_e32 v26, 56, v2
	s_add_i32 s0, s4, 0
	v_mul_u32_u24_e32 v2, 0x84, v26
	v_lshlrev_b32_e32 v13, 2, v19
	v_mov_b32_e32 v3, 0
	v_add3_u32 v44, s0, v2, v13
	v_lshlrev_b32_e32 v2, 1, v26
	v_lshl_add_u64 v[10:11], s[28:29], 0, v[2:3]
	s_mov_b64 s[0:1], 0x2900000
	v_lshl_add_u64 v[4:5], v[10:11], 0, s[0:1]
	s_mov_b64 s[0:1], 0x2300000
	s_lshl_b32 s15, s14, 3
	v_lshl_add_u64 v[6:7], v[10:11], 0, s[0:1]
	s_mov_b64 s[0:1], 0x1d80000
	s_add_u32 s18, s28, 0x2e00000
	v_lshl_add_u64 v[8:9], v[10:11], 0, s[0:1]
	s_mov_b64 s[0:1], 0x1280000
	s_addc_u32 s19, s29, 0
	v_lshl_add_u64 v[10:11], v[10:11], 0, s[0:1]
	s_lshl_b32 s0, s2, 3
	v_lshrrev_b32_e32 v1, 5, v164
	v_mov_b32_e32 v2, 0x6000
	s_add_i32 s0, s33, s0
	s_lshl_b32 s1, s12, 3
	v_and_b32_e32 v12, 31, v0
	v_lshl_or_b32 v49, v19, 13, v2
	v_mul_u32_u24_e32 v2, 0x84, v1
	s_sub_i32 s0, s0, s1
	v_and_b32_e32 v48, 16, v13
	v_or_b32_e32 v55, 0x80c, v13
	v_or_b32_e32 v56, 12, v13
	v_or_b32_e32 v13, s4, v2
	v_lshlrev_b32_e32 v2, 2, v12
	s_add_i32 s20, s0, 0xffffe780
	s_lshl_b32 s0, s3, 8
	s_lshl_b32 s1, s12, 8
	v_bfe_u32 v18, v0, 5, 1
	v_add3_u32 v57, v13, v2, 0
	v_lshl_add_u64 v[12:13], s[60:61], 0, v[2:3]
	s_sub_i32 s22, s0, s1
	s_lshl_b32 s0, s3, 5
	s_lshl_b32 s1, s12, 5
	v_readlane_b32 s60, v244, 0
	v_mul_u32_u24_e32 v20, 0x3000, v18
	s_sub_i32 s24, s0, s1
	v_readlane_b32 s61, v244, 1
	v_readlane_b32 s64, v244, 4
	v_readlane_b32 s65, v244, 5
	s_lshl_b32 s0, s13, 1
	s_lshl_b32 s1, s3, 4
	s_lshl_b32 s4, s12, 4
	v_mul_hi_u32_u24_e32 v21, 0x3000, v18
	v_or_b32_e32 v20, v20, v2
	s_mov_b32 s5, 0
	v_or_b32_e32 v45, 8, v19
	v_or_b32_e32 v46, 16, v19
	v_or_b32_e32 v47, 24, v19
	v_or_b32_e32 v50, 0x800, v48
	v_or_b32_e32 v51, 0x804, v48
	v_or_b32_e32 v52, 4, v48
	v_or_b32_e32 v53, 0x808, v48
	v_or_b32_e32 v54, 8, v48
	s_lshl_b32 s21, s13, 5
	v_or_b32_e32 v58, 14, v1
	s_lshl_b32 s23, s13, 2
	v_or_b32_e32 v59, 12, v1
	v_or_b32_e32 v60, 10, v1
	v_or_b32_e32 v61, 8, v1
	v_or_b32_e32 v62, 6, v1
	v_or_b32_e32 v63, 4, v1
	v_or_b32_e32 v64, 2, v1
	v_lshl_add_u64 v[14:15], s[64:65], 0, v[2:3]
	s_add_i32 s25, s0, 0x7fffd300
	s_sub_i32 s26, s1, s4
	v_lshl_add_u64 v[16:17], s[48:49], 0, v[2:3]
	v_lshl_add_u64 v[20:21], s[48:49], 0, v[20:21]
	v_lshl_add_u64 v[22:23], s[46:47], 0, v[2:3]
	s_add_i32 s27, s0, 0x7fffea00
	v_lshl_add_u64 v[24:25], s[44:45], 0, v[2:3]
	s_movk_i32 s44, 0xaff
	v_lshlrev_b32_e32 v26, 1, v26
	s_movk_i32 s45, 0x3e3
	s_movk_i32 s46, 0x2000
	s_movk_i32 s47, 0x4000
	s_mov_b32 s48, 0x1f1800
	s_movk_i32 s49, 0x7e3
	s_movk_i32 s56, 0x5000
	s_mov_b32 s57, 0xb000
	s_movk_i32 s60, 0x5800
	v_mov_b32_e32 v65, 0x3e3
	v_mov_b32_e32 v66, 0x5800
	v_mov_b32_e32 v67, 0xfffff500
	v_mov_b32_e32 v68, 0x80
	v_mov_b32_e32 v69, 0x63
	s_mov_b32 s61, s13
	v_readlane_b32 s62, v244, 2
	v_readlane_b32 s63, v244, 3
	v_readlane_b32 s66, v244, 6
	v_readlane_b32 s67, v244, 7
	s_branch .Ld1c_268

.Ld1c_268:
	s_cmpk_gt_i32 s61, 0xaff
	s_mov_b64 s[0:1], -1
	s_cbranch_scc0 .Ld1c_267
	s_lshl_b32 s0, s21, 2
	s_and_b32 s10, s0, 0xf80
	s_cmpk_gt_u32 s61, 0x107f
	s_mov_b64 s[0:1], -1
	s_cbranch_scc0 .Ld1c_309
	s_branch .Ld1c_end
	s_cmpk_gt_u32 s61, 0x167f
	s_cbranch_scc0 .Ld1c_280
	s_cmpk_gt_u32 s61, 0x187f
	s_cbranch_scc0 .Ld1c_275
	s_lshr_b32 s8, s21, 5
	s_lshr_b32 s4, s20, 7
	s_lshl_b64 s[0:1], s[4:5], 20
	s_and_b32 s4, s8, 15
	s_lshl_b32 s4, s4, 7
	s_or_b32 s0, s0, s4
	s_and_b32 s4, s23, 0x1c0
	v_or_b32_e32 v2, s4, v58
	v_lshl_or_b32 v42, v2, 11, s0
	v_mov_b32_e32 v43, s1
	v_or_b32_e32 v2, s4, v59
	v_lshl_add_u64 v[28:29], v[12:13], 0, v[42:43]
	v_lshl_or_b32 v42, v2, 11, s0
	v_or_b32_e32 v2, s4, v60
	v_lshl_add_u64 v[30:31], v[12:13], 0, v[42:43]
	v_lshl_or_b32 v42, v2, 11, s0
	v_or_b32_e32 v2, s4, v61
	v_lshl_add_u64 v[32:33], v[12:13], 0, v[42:43]
	v_lshl_or_b32 v42, v2, 11, s0
	v_or_b32_e32 v2, s4, v62
	v_lshl_add_u64 v[34:35], v[12:13], 0, v[42:43]
	v_lshl_or_b32 v42, v2, 11, s0
	v_or_b32_e32 v2, s4, v63
	v_lshl_add_u64 v[36:37], v[12:13], 0, v[42:43]
	v_lshl_or_b32 v42, v2, 11, s0
	v_or_b32_e32 v2, s4, v64
	v_lshl_add_u64 v[38:39], v[12:13], 0, v[42:43]
	v_lshl_or_b32 v42, v2, 11, s0
	v_or_b32_e32 v2, s4, v1
	v_lshl_add_u64 v[40:41], v[12:13], 0, v[42:43]
	v_lshl_or_b32 v42, v2, 11, s0
	v_lshl_add_u64 v[42:43], v[12:13], 0, v[42:43]
	s_mov_b64 s[0:1], 0
	v_mov_b32_e32 v2, v57
